# s_sleep 1 at the start of every GEMM load segment (after the MFMA-end barrier), on top of v26
# baseline (speedup 1.0000x reference)
.Lpeela:
	ds_read_b128 v[130:133], v208
	ds_read_b128 v[134:137], v208 offset:1024
	ds_read_b128 v[138:141], v208 offset:2048
	ds_read_b128 v[142:145], v208 offset:3072
	ds_read_b128 v[146:149], v209
	ds_read_b128 v[150:153], v209 offset:1024
	ds_read_b128 v[154:157], v209 offset:2048
	ds_read_b128 v[158:161], v209 offset:3072
	s_add_u32 s52, s50, 0xfff00080
	s_addc_u32 s53, s51, -1
	s_cmp_eq_u32 s89, 60
	s_cselect_b32 s55, s43, s53
	s_cselect_b32 s54, s85, s52
	s_cselect_b32 s53, s41, s88
	s_cselect_b32 s52, s86, s87
	v_lshl_add_u64 v[204:205], s[50:51], 0, v[192:193]
	s_add_i32 m0, s56, 0xc000
	ds_read_b128 v[162:165], v210
	ds_read_b128 v[166:169], v210 offset:1024
	ds_read_b128 v[170:173], v210 offset:2048
	ds_read_b128 v[174:177], v210 offset:3072
	ds_read_b128 v[200:203], v210 offset:4096
	ds_read_b128 v[212:215], v210 offset:5120
	ds_read_b128 v[216:219], v210 offset:6144
	ds_read_b128 v[224:227], v210 offset:7168
	global_load_lds_dwordx4 v[204:205], off
	v_lshl_add_u64 v[204:205], s[50:51], 0, v[194:195]
	s_add_i32 m0, s56, 0xe000
	s_nop 0
	global_load_lds_dwordx4 v[204:205], off
	s_waitcnt vmcnt(8)
	s_waitcnt lgkmcnt(0)
	s_setprio 1
	s_barrier
	v_mfma_f32_16x16x32_bf16 v[126:129], v[130:133], v[162:165], 0
	v_mfma_f32_16x16x32_bf16 v[122:125], v[138:141], v[162:165], 0
	v_mfma_f32_16x16x32_bf16 v[110:113], v[130:133], v[170:173], 0
	v_mfma_f32_16x16x32_bf16 v[106:109], v[138:141], v[170:173], 0
	v_mfma_f32_16x16x32_bf16 v[94:97], v[130:133], v[200:203], 0
	v_mfma_f32_16x16x32_bf16 v[90:93], v[138:141], v[200:203], 0
	v_mfma_f32_16x16x32_bf16 v[78:81], v[130:133], v[216:219], 0
	v_mfma_f32_16x16x32_bf16 v[74:77], v[138:141], v[216:219], 0
	v_mfma_f32_16x16x32_bf16 v[126:129], v[134:137], v[166:169], v[126:129]
	v_mfma_f32_16x16x32_bf16 v[122:125], v[142:145], v[166:169], v[122:125]
	v_mfma_f32_16x16x32_bf16 v[110:113], v[134:137], v[174:177], v[110:113]
	v_mfma_f32_16x16x32_bf16 v[106:109], v[142:145], v[174:177], v[106:109]
	v_mfma_f32_16x16x32_bf16 v[94:97], v[134:137], v[212:215], v[94:97]
	v_mfma_f32_16x16x32_bf16 v[90:93], v[142:145], v[212:215], v[90:93]
	v_mfma_f32_16x16x32_bf16 v[78:81], v[134:137], v[224:227], v[78:81]
	v_mfma_f32_16x16x32_bf16 v[74:77], v[142:145], v[224:227], v[74:77]
	v_mfma_f32_16x16x32_bf16 v[118:121], v[146:149], v[162:165], 0
	v_mfma_f32_16x16x32_bf16 v[114:117], v[154:157], v[162:165], 0
	v_mfma_f32_16x16x32_bf16 v[102:105], v[146:149], v[170:173], 0
	v_mfma_f32_16x16x32_bf16 v[98:101], v[154:157], v[170:173], 0
	v_mfma_f32_16x16x32_bf16 v[86:89], v[146:149], v[200:203], 0
	v_mfma_f32_16x16x32_bf16 v[82:85], v[154:157], v[200:203], 0
	v_mfma_f32_16x16x32_bf16 v[70:73], v[146:149], v[216:219], 0
	v_mfma_f32_16x16x32_bf16 v[66:69], v[154:157], v[216:219], 0
	v_mfma_f32_16x16x32_bf16 v[118:121], v[150:153], v[166:169], v[118:121]
	v_mfma_f32_16x16x32_bf16 v[114:117], v[158:161], v[166:169], v[114:117]
	v_mfma_f32_16x16x32_bf16 v[102:105], v[150:153], v[174:177], v[102:105]
	v_mfma_f32_16x16x32_bf16 v[98:101], v[158:161], v[174:177], v[98:101]
	v_mfma_f32_16x16x32_bf16 v[86:89], v[150:153], v[212:215], v[86:89]
	v_mfma_f32_16x16x32_bf16 v[82:85], v[158:161], v[212:215], v[82:85]
	v_mfma_f32_16x16x32_bf16 v[70:73], v[150:153], v[224:227], v[70:73]
	v_mfma_f32_16x16x32_bf16 v[66:69], v[158:161], v[224:227], v[66:69]
	s_barrier
	s_setprio 0
	s_sleep 1
	s_add_i32 s90, s65, s31
	v_lshl_add_u64 v[204:205], s[52:53], 0, v[182:183]
	s_mov_b32 m0, s90
	ds_read_b128 v[162:165], v210 offset:16384
	ds_read_b128 v[166:169], v210 offset:17408
	ds_read_b128 v[170:173], v210 offset:18432
	ds_read_b128 v[174:177], v210 offset:19456
	ds_read_b128 v[200:203], v210 offset:20480
	ds_read_b128 v[212:215], v210 offset:21504
	ds_read_b128 v[216:219], v210 offset:22528
	ds_read_b128 v[224:227], v210 offset:23552
	global_load_lds_dwordx4 v[204:205], off
	s_add_i32 m0, s90, 0x2000
	s_add_u32 s90, s52, 0x100000
	v_lshl_add_u64 v[220:221], s[52:53], 0, v[178:179]
	s_addc_u32 s91, s53, 0
	s_add_i32 s92, s66, s31
	global_load_lds_dwordx4 v[220:221], off
	v_lshl_add_u64 v[228:229], s[90:91], 0, v[182:183]
	s_mov_b32 m0, s92
	v_lshl_add_u64 v[230:231], s[54:55], 0, v[180:181]
	global_load_lds_dwordx4 v[228:229], off
	v_lshl_add_u64 v[228:229], s[90:91], 0, v[178:179]
	s_add_i32 m0, s92, 0x2000
	s_nop 0
	global_load_lds_dwordx4 v[228:229], off
	v_lshl_add_u64 v[228:229], s[54:55], 0, v[184:185]
	s_mov_b32 m0, s56
	s_nop 0
	global_load_lds_dwordx4 v[228:229], off
	s_mov_b32 m0, s57
	s_nop 0
	global_load_lds_dwordx4 v[230:231], off
	s_waitcnt vmcnt(8)
	s_waitcnt lgkmcnt(0)
	s_setprio 1
	s_barrier
	v_mfma_f32_16x16x32_bf16 v[62:65], v[130:133], v[162:165], 0
	v_mfma_f32_16x16x32_bf16 v[58:61], v[138:141], v[162:165], 0
	v_mfma_f32_16x16x32_bf16 v[50:53], v[130:133], v[170:173], 0
	v_mfma_f32_16x16x32_bf16 v[42:45], v[138:141], v[170:173], 0
	v_mfma_f32_16x16x32_bf16 v[34:37], v[130:133], v[200:203], 0
	v_mfma_f32_16x16x32_bf16 v[26:29], v[138:141], v[200:203], 0
	v_mfma_f32_16x16x32_bf16 v[18:21], v[130:133], v[216:219], 0
	v_mfma_f32_16x16x32_bf16 v[10:13], v[138:141], v[216:219], 0
	v_mfma_f32_16x16x32_bf16 v[62:65], v[134:137], v[166:169], v[62:65]
	v_mfma_f32_16x16x32_bf16 v[58:61], v[142:145], v[166:169], v[58:61]
	v_mfma_f32_16x16x32_bf16 v[50:53], v[134:137], v[174:177], v[50:53]
	v_mfma_f32_16x16x32_bf16 v[42:45], v[142:145], v[174:177], v[42:45]
	v_mfma_f32_16x16x32_bf16 v[34:37], v[134:137], v[212:215], v[34:37]
	v_mfma_f32_16x16x32_bf16 v[26:29], v[142:145], v[212:215], v[26:29]
	v_mfma_f32_16x16x32_bf16 v[18:21], v[134:137], v[224:227], v[18:21]
	v_mfma_f32_16x16x32_bf16 v[10:13], v[142:145], v[224:227], v[10:13]
	v_mfma_f32_16x16x32_bf16 v[54:57], v[146:149], v[162:165], 0
	v_mfma_f32_16x16x32_bf16 v[46:49], v[154:157], v[162:165], 0
	v_mfma_f32_16x16x32_bf16 v[38:41], v[146:149], v[170:173], 0
	v_mfma_f32_16x16x32_bf16 v[30:33], v[154:157], v[170:173], 0
	v_mfma_f32_16x16x32_bf16 v[22:25], v[146:149], v[200:203], 0
	v_mfma_f32_16x16x32_bf16 v[14:17], v[154:157], v[200:203], 0
	v_mfma_f32_16x16x32_bf16 v[6:9], v[146:149], v[216:219], 0
	v_mfma_f32_16x16x32_bf16 v[2:5], v[154:157], v[216:219], 0
	v_mfma_f32_16x16x32_bf16 v[54:57], v[150:153], v[166:169], v[54:57]
	v_mfma_f32_16x16x32_bf16 v[46:49], v[158:161], v[166:169], v[46:49]
	v_mfma_f32_16x16x32_bf16 v[38:41], v[150:153], v[174:177], v[38:41]
	v_mfma_f32_16x16x32_bf16 v[30:33], v[158:161], v[174:177], v[30:33]
	v_mfma_f32_16x16x32_bf16 v[22:25], v[150:153], v[212:215], v[22:25]
	v_mfma_f32_16x16x32_bf16 v[14:17], v[158:161], v[212:215], v[14:17]
	v_mfma_f32_16x16x32_bf16 v[6:9], v[150:153], v[224:227], v[6:9]
	v_mfma_f32_16x16x32_bf16 v[2:5], v[158:161], v[224:227], v[2:5]
	s_barrier
	s_setprio 0
	s_sleep 1
	s_add_i32 s90, 0, 0x18000
	s_add_i32 s91, 0, 0x1c000
	v_add_u32_e32 v142, s90, v189
	v_add_u32_e32 v158, s91, v189
	ds_read_b128 v[130:133], v142
	ds_read_b128 v[134:137], v142 offset:1024
	ds_read_b128 v[138:141], v142 offset:2048
	ds_read_b128 v[142:145], v142 offset:3072
	ds_read_b128 v[146:149], v158
	ds_read_b128 v[150:153], v158 offset:1024
	ds_read_b128 v[154:157], v158 offset:2048
	ds_read_b128 v[158:161], v158 offset:3072
	s_add_u32 s54, s54, 0x100000
	s_addc_u32 s55, s55, 0
	s_mov_b32 m0, s58
	v_lshl_add_u64 v[232:233], s[54:55], 0, v[184:185]
	ds_read_b128 v[162:165], v210 offset:32768
	ds_read_b128 v[166:169], v210 offset:33792
	ds_read_b128 v[170:173], v210 offset:34816
	ds_read_b128 v[174:177], v210 offset:35840
	ds_read_b128 v[200:203], v210 offset:36864
	ds_read_b128 v[212:215], v210 offset:37888
	ds_read_b128 v[216:219], v210 offset:38912
	ds_read_b128 v[224:227], v210 offset:39936
	global_load_lds_dwordx4 v[232:233], off
	v_lshl_add_u64 v[232:233], s[54:55], 0, v[180:181]
	s_mov_b32 m0, s59
	s_nop 0
	global_load_lds_dwordx4 v[232:233], off
	s_waitcnt vmcnt(8)
	s_waitcnt lgkmcnt(0)
	s_setprio 1
	s_barrier
	v_mfma_f32_16x16x32_bf16 v[126:129], v[130:133], v[162:165], v[126:129]
	v_mfma_f32_16x16x32_bf16 v[122:125], v[138:141], v[162:165], v[122:125]
	v_mfma_f32_16x16x32_bf16 v[110:113], v[130:133], v[170:173], v[110:113]
	v_mfma_f32_16x16x32_bf16 v[106:109], v[138:141], v[170:173], v[106:109]
	v_mfma_f32_16x16x32_bf16 v[94:97], v[130:133], v[200:203], v[94:97]
	v_mfma_f32_16x16x32_bf16 v[90:93], v[138:141], v[200:203], v[90:93]
	v_mfma_f32_16x16x32_bf16 v[78:81], v[130:133], v[216:219], v[78:81]
	v_mfma_f32_16x16x32_bf16 v[74:77], v[138:141], v[216:219], v[74:77]
	v_mfma_f32_16x16x32_bf16 v[126:129], v[134:137], v[166:169], v[126:129]
	v_mfma_f32_16x16x32_bf16 v[122:125], v[142:145], v[166:169], v[122:125]
	v_mfma_f32_16x16x32_bf16 v[110:113], v[134:137], v[174:177], v[110:113]
	v_mfma_f32_16x16x32_bf16 v[106:109], v[142:145], v[174:177], v[106:109]
	v_mfma_f32_16x16x32_bf16 v[94:97], v[134:137], v[212:215], v[94:97]
	v_mfma_f32_16x16x32_bf16 v[90:93], v[142:145], v[212:215], v[90:93]
	v_mfma_f32_16x16x32_bf16 v[78:81], v[134:137], v[224:227], v[78:81]
	v_mfma_f32_16x16x32_bf16 v[74:77], v[142:145], v[224:227], v[74:77]
	v_mfma_f32_16x16x32_bf16 v[118:121], v[146:149], v[162:165], v[118:121]
	v_mfma_f32_16x16x32_bf16 v[114:117], v[154:157], v[162:165], v[114:117]
	v_mfma_f32_16x16x32_bf16 v[102:105], v[146:149], v[170:173], v[102:105]
	v_mfma_f32_16x16x32_bf16 v[98:101], v[154:157], v[170:173], v[98:101]
	v_mfma_f32_16x16x32_bf16 v[86:89], v[146:149], v[200:203], v[86:89]
	v_mfma_f32_16x16x32_bf16 v[82:85], v[154:157], v[200:203], v[82:85]
	v_mfma_f32_16x16x32_bf16 v[70:73], v[146:149], v[216:219], v[70:73]
	v_mfma_f32_16x16x32_bf16 v[66:69], v[154:157], v[216:219], v[66:69]
	v_mfma_f32_16x16x32_bf16 v[118:121], v[150:153], v[166:169], v[118:121]
	v_mfma_f32_16x16x32_bf16 v[114:117], v[158:161], v[166:169], v[114:117]
	v_mfma_f32_16x16x32_bf16 v[102:105], v[150:153], v[174:177], v[102:105]
	v_mfma_f32_16x16x32_bf16 v[98:101], v[158:161], v[174:177], v[98:101]
	v_mfma_f32_16x16x32_bf16 v[86:89], v[150:153], v[212:215], v[86:89]
	v_mfma_f32_16x16x32_bf16 v[82:85], v[158:161], v[212:215], v[82:85]
	v_mfma_f32_16x16x32_bf16 v[70:73], v[150:153], v[224:227], v[70:73]
	v_mfma_f32_16x16x32_bf16 v[66:69], v[158:161], v[224:227], v[66:69]
	s_barrier
	s_setprio 0
	s_sleep 1
	s_add_i32 s54, s90, s31
	v_lshl_add_u64 v[204:205], v[204:205], 0, s[8:9]
	s_mov_b32 m0, s54
	ds_read_b128 v[162:165], v210 offset:49152
	ds_read_b128 v[166:169], v210 offset:50176
	ds_read_b128 v[170:173], v210 offset:51200
	ds_read_b128 v[174:177], v210 offset:52224
	ds_read_b128 v[200:203], v210 offset:53248
	ds_read_b128 v[212:215], v210 offset:54272
	ds_read_b128 v[216:219], v210 offset:55296
	ds_read_b128 v[224:227], v210 offset:56320
	global_load_lds_dwordx4 v[204:205], off
	s_add_i32 m0, s54, 0x2000
	s_add_u32 s52, s52, 0x100080
	v_lshl_add_u64 v[204:205], v[220:221], 0, s[8:9]
	s_addc_u32 s53, s53, 0
	s_add_i32 s54, s91, s31
	global_load_lds_dwordx4 v[204:205], off
	v_lshl_add_u64 v[204:205], s[52:53], 0, v[182:183]
	s_mov_b32 m0, s54
	s_nop 0
	global_load_lds_dwordx4 v[204:205], off
	v_lshl_add_u64 v[204:205], s[52:53], 0, v[178:179]
	s_add_i32 m0, s54, 0x2000
	s_nop 0
	global_load_lds_dwordx4 v[204:205], off
	v_lshl_add_u64 v[204:205], v[228:229], 0, s[8:9]
	s_mov_b32 m0, s62
	s_nop 0
	global_load_lds_dwordx4 v[204:205], off
	v_lshl_add_u64 v[204:205], v[230:231], 0, s[8:9]
	s_mov_b32 m0, s63
	s_nop 0
	global_load_lds_dwordx4 v[204:205], off
	s_waitcnt vmcnt(8)
	s_waitcnt lgkmcnt(0)
	s_setprio 1
	s_barrier
	v_mfma_f32_16x16x32_bf16 v[62:65], v[130:133], v[162:165], v[62:65]
	v_mfma_f32_16x16x32_bf16 v[58:61], v[138:141], v[162:165], v[58:61]
	v_mfma_f32_16x16x32_bf16 v[50:53], v[130:133], v[170:173], v[50:53]
	v_mfma_f32_16x16x32_bf16 v[42:45], v[138:141], v[170:173], v[42:45]
	v_mfma_f32_16x16x32_bf16 v[34:37], v[130:133], v[200:203], v[34:37]
	v_mfma_f32_16x16x32_bf16 v[26:29], v[138:141], v[200:203], v[26:29]
	v_mfma_f32_16x16x32_bf16 v[18:21], v[130:133], v[216:219], v[18:21]
	v_mfma_f32_16x16x32_bf16 v[10:13], v[138:141], v[216:219], v[10:13]
	v_mfma_f32_16x16x32_bf16 v[62:65], v[134:137], v[166:169], v[62:65]
	v_mfma_f32_16x16x32_bf16 v[58:61], v[142:145], v[166:169], v[58:61]
	v_mfma_f32_16x16x32_bf16 v[50:53], v[134:137], v[174:177], v[50:53]
	v_mfma_f32_16x16x32_bf16 v[42:45], v[142:145], v[174:177], v[42:45]
	v_mfma_f32_16x16x32_bf16 v[34:37], v[134:137], v[212:215], v[34:37]
	v_mfma_f32_16x16x32_bf16 v[26:29], v[142:145], v[212:215], v[26:29]
	v_mfma_f32_16x16x32_bf16 v[18:21], v[134:137], v[224:227], v[18:21]
	v_mfma_f32_16x16x32_bf16 v[10:13], v[142:145], v[224:227], v[10:13]
	v_mfma_f32_16x16x32_bf16 v[54:57], v[146:149], v[162:165], v[54:57]
	v_mfma_f32_16x16x32_bf16 v[46:49], v[154:157], v[162:165], v[46:49]
	v_mfma_f32_16x16x32_bf16 v[38:41], v[146:149], v[170:173], v[38:41]
	v_mfma_f32_16x16x32_bf16 v[30:33], v[154:157], v[170:173], v[30:33]
	v_mfma_f32_16x16x32_bf16 v[22:25], v[146:149], v[200:203], v[22:25]
	v_mfma_f32_16x16x32_bf16 v[14:17], v[154:157], v[200:203], v[14:17]
	v_mfma_f32_16x16x32_bf16 v[6:9], v[146:149], v[216:219], v[6:9]
	v_mfma_f32_16x16x32_bf16 v[2:5], v[154:157], v[216:219], v[2:5]
	v_mfma_f32_16x16x32_bf16 v[54:57], v[150:153], v[166:169], v[54:57]
	v_mfma_f32_16x16x32_bf16 v[46:49], v[158:161], v[166:169], v[46:49]
	v_mfma_f32_16x16x32_bf16 v[38:41], v[150:153], v[174:177], v[38:41]
	v_mfma_f32_16x16x32_bf16 v[30:33], v[158:161], v[174:177], v[30:33]
	v_mfma_f32_16x16x32_bf16 v[22:25], v[150:153], v[212:215], v[22:25]
	v_mfma_f32_16x16x32_bf16 v[14:17], v[158:161], v[212:215], v[14:17]
	v_mfma_f32_16x16x32_bf16 v[6:9], v[150:153], v[224:227], v[6:9]
	v_mfma_f32_16x16x32_bf16 v[2:5], v[158:161], v[224:227], v[2:5]
	s_barrier
	s_setprio 0
	s_sleep 1
	s_add_i32 s89, s89, 2
	s_add_u32 s50, s50, 0x100
	s_addc_u32 s51, s51, 0
	s_add_u32 s87, s87, 0x100
	s_addc_u32 s88, s88, 0
.LBB0_224:
	ds_read_b128 v[130:133], v208
	ds_read_b128 v[134:137], v208 offset:1024
	ds_read_b128 v[138:141], v208 offset:2048
	ds_read_b128 v[142:145], v208 offset:3072
	ds_read_b128 v[146:149], v209
	ds_read_b128 v[150:153], v209 offset:1024
	ds_read_b128 v[154:157], v209 offset:2048
	ds_read_b128 v[158:161], v209 offset:3072
	s_add_u32 s52, s50, 0xfff00080
	s_addc_u32 s53, s51, -1
	s_cmp_eq_u32 s89, 60
	s_cselect_b32 s55, s43, s53
	s_cselect_b32 s54, s85, s52
	s_cselect_b32 s53, s41, s88
	s_cselect_b32 s52, s86, s87
	v_lshl_add_u64 v[204:205], s[50:51], 0, v[192:193]
	s_add_i32 m0, s56, 0xc000
	ds_read_b128 v[162:165], v210
	ds_read_b128 v[166:169], v210 offset:1024
	ds_read_b128 v[170:173], v210 offset:2048
	ds_read_b128 v[174:177], v210 offset:3072
	ds_read_b128 v[200:203], v210 offset:4096
	ds_read_b128 v[212:215], v210 offset:5120
	ds_read_b128 v[216:219], v210 offset:6144
	ds_read_b128 v[224:227], v210 offset:7168
	global_load_lds_dwordx4 v[204:205], off
	v_lshl_add_u64 v[204:205], s[50:51], 0, v[194:195]
	s_add_i32 m0, s56, 0xe000
	s_nop 0
	global_load_lds_dwordx4 v[204:205], off
	s_waitcnt vmcnt(8)
	s_waitcnt lgkmcnt(0)
	s_setprio 1
	s_barrier
	v_mfma_f32_16x16x32_bf16 v[126:129], v[130:133], v[162:165], v[126:129]
	v_mfma_f32_16x16x32_bf16 v[122:125], v[138:141], v[162:165], v[122:125]
	v_mfma_f32_16x16x32_bf16 v[110:113], v[130:133], v[170:173], v[110:113]
	v_mfma_f32_16x16x32_bf16 v[106:109], v[138:141], v[170:173], v[106:109]
	v_mfma_f32_16x16x32_bf16 v[94:97], v[130:133], v[200:203], v[94:97]
	v_mfma_f32_16x16x32_bf16 v[90:93], v[138:141], v[200:203], v[90:93]
	v_mfma_f32_16x16x32_bf16 v[78:81], v[130:133], v[216:219], v[78:81]
	v_mfma_f32_16x16x32_bf16 v[74:77], v[138:141], v[216:219], v[74:77]
	v_mfma_f32_16x16x32_bf16 v[126:129], v[134:137], v[166:169], v[126:129]
	v_mfma_f32_16x16x32_bf16 v[122:125], v[142:145], v[166:169], v[122:125]
	v_mfma_f32_16x16x32_bf16 v[110:113], v[134:137], v[174:177], v[110:113]
	v_mfma_f32_16x16x32_bf16 v[106:109], v[142:145], v[174:177], v[106:109]
	v_mfma_f32_16x16x32_bf16 v[94:97], v[134:137], v[212:215], v[94:97]
	v_mfma_f32_16x16x32_bf16 v[90:93], v[142:145], v[212:215], v[90:93]
	v_mfma_f32_16x16x32_bf16 v[78:81], v[134:137], v[224:227], v[78:81]
	v_mfma_f32_16x16x32_bf16 v[74:77], v[142:145], v[224:227], v[74:77]
	v_mfma_f32_16x16x32_bf16 v[118:121], v[146:149], v[162:165], v[118:121]
	v_mfma_f32_16x16x32_bf16 v[114:117], v[154:157], v[162:165], v[114:117]
	v_mfma_f32_16x16x32_bf16 v[102:105], v[146:149], v[170:173], v[102:105]
	v_mfma_f32_16x16x32_bf16 v[98:101], v[154:157], v[170:173], v[98:101]
	v_mfma_f32_16x16x32_bf16 v[86:89], v[146:149], v[200:203], v[86:89]
	v_mfma_f32_16x16x32_bf16 v[82:85], v[154:157], v[200:203], v[82:85]
	v_mfma_f32_16x16x32_bf16 v[70:73], v[146:149], v[216:219], v[70:73]
	v_mfma_f32_16x16x32_bf16 v[66:69], v[154:157], v[216:219], v[66:69]
	v_mfma_f32_16x16x32_bf16 v[118:121], v[150:153], v[166:169], v[118:121]
	v_mfma_f32_16x16x32_bf16 v[114:117], v[158:161], v[166:169], v[114:117]
	v_mfma_f32_16x16x32_bf16 v[102:105], v[150:153], v[174:177], v[102:105]
	v_mfma_f32_16x16x32_bf16 v[98:101], v[158:161], v[174:177], v[98:101]
	v_mfma_f32_16x16x32_bf16 v[86:89], v[150:153], v[212:215], v[86:89]
	v_mfma_f32_16x16x32_bf16 v[82:85], v[158:161], v[212:215], v[82:85]
	v_mfma_f32_16x16x32_bf16 v[70:73], v[150:153], v[224:227], v[70:73]
	v_mfma_f32_16x16x32_bf16 v[66:69], v[158:161], v[224:227], v[66:69]
	s_barrier
	s_setprio 0
	s_sleep 1
	s_add_i32 s90, s65, s31
	v_lshl_add_u64 v[204:205], s[52:53], 0, v[182:183]
	s_mov_b32 m0, s90
	ds_read_b128 v[162:165], v210 offset:16384
	ds_read_b128 v[166:169], v210 offset:17408
	ds_read_b128 v[170:173], v210 offset:18432
	ds_read_b128 v[174:177], v210 offset:19456
	ds_read_b128 v[200:203], v210 offset:20480
	ds_read_b128 v[212:215], v210 offset:21504
	ds_read_b128 v[216:219], v210 offset:22528
	ds_read_b128 v[224:227], v210 offset:23552
	global_load_lds_dwordx4 v[204:205], off
	s_add_i32 m0, s90, 0x2000
	s_add_u32 s90, s52, 0x100000
	v_lshl_add_u64 v[220:221], s[52:53], 0, v[178:179]
	s_addc_u32 s91, s53, 0
	s_add_i32 s92, s66, s31
	global_load_lds_dwordx4 v[220:221], off
	v_lshl_add_u64 v[228:229], s[90:91], 0, v[182:183]
	s_mov_b32 m0, s92
	v_lshl_add_u64 v[230:231], s[54:55], 0, v[180:181]
	global_load_lds_dwordx4 v[228:229], off
	v_lshl_add_u64 v[228:229], s[90:91], 0, v[178:179]
	s_add_i32 m0, s92, 0x2000
	s_nop 0
	global_load_lds_dwordx4 v[228:229], off
	v_lshl_add_u64 v[228:229], s[54:55], 0, v[184:185]
	s_mov_b32 m0, s56
	s_nop 0
	global_load_lds_dwordx4 v[228:229], off
	s_mov_b32 m0, s57
	s_nop 0
	global_load_lds_dwordx4 v[230:231], off
	s_waitcnt vmcnt(8)
	s_waitcnt lgkmcnt(0)
	s_setprio 1
	s_barrier
	v_mfma_f32_16x16x32_bf16 v[62:65], v[130:133], v[162:165], v[62:65]
	v_mfma_f32_16x16x32_bf16 v[58:61], v[138:141], v[162:165], v[58:61]
	v_mfma_f32_16x16x32_bf16 v[50:53], v[130:133], v[170:173], v[50:53]
	v_mfma_f32_16x16x32_bf16 v[42:45], v[138:141], v[170:173], v[42:45]
	v_mfma_f32_16x16x32_bf16 v[34:37], v[130:133], v[200:203], v[34:37]
	v_mfma_f32_16x16x32_bf16 v[26:29], v[138:141], v[200:203], v[26:29]
	v_mfma_f32_16x16x32_bf16 v[18:21], v[130:133], v[216:219], v[18:21]
	v_mfma_f32_16x16x32_bf16 v[10:13], v[138:141], v[216:219], v[10:13]
	v_mfma_f32_16x16x32_bf16 v[62:65], v[134:137], v[166:169], v[62:65]
	v_mfma_f32_16x16x32_bf16 v[58:61], v[142:145], v[166:169], v[58:61]
	v_mfma_f32_16x16x32_bf16 v[50:53], v[134:137], v[174:177], v[50:53]
	v_mfma_f32_16x16x32_bf16 v[42:45], v[142:145], v[174:177], v[42:45]
	v_mfma_f32_16x16x32_bf16 v[34:37], v[134:137], v[212:215], v[34:37]
	v_mfma_f32_16x16x32_bf16 v[26:29], v[142:145], v[212:215], v[26:29]
	v_mfma_f32_16x16x32_bf16 v[18:21], v[134:137], v[224:227], v[18:21]
	v_mfma_f32_16x16x32_bf16 v[10:13], v[142:145], v[224:227], v[10:13]
	v_mfma_f32_16x16x32_bf16 v[54:57], v[146:149], v[162:165], v[54:57]
	v_mfma_f32_16x16x32_bf16 v[46:49], v[154:157], v[162:165], v[46:49]
	v_mfma_f32_16x16x32_bf16 v[38:41], v[146:149], v[170:173], v[38:41]
	v_mfma_f32_16x16x32_bf16 v[30:33], v[154:157], v[170:173], v[30:33]
	v_mfma_f32_16x16x32_bf16 v[22:25], v[146:149], v[200:203], v[22:25]
	v_mfma_f32_16x16x32_bf16 v[14:17], v[154:157], v[200:203], v[14:17]
	v_mfma_f32_16x16x32_bf16 v[6:9], v[146:149], v[216:219], v[6:9]
	v_mfma_f32_16x16x32_bf16 v[2:5], v[154:157], v[216:219], v[2:5]
	v_mfma_f32_16x16x32_bf16 v[54:57], v[150:153], v[166:169], v[54:57]
	v_mfma_f32_16x16x32_bf16 v[46:49], v[158:161], v[166:169], v[46:49]
	v_mfma_f32_16x16x32_bf16 v[38:41], v[150:153], v[174:177], v[38:41]
	v_mfma_f32_16x16x32_bf16 v[30:33], v[158:161], v[174:177], v[30:33]
	v_mfma_f32_16x16x32_bf16 v[22:25], v[150:153], v[212:215], v[22:25]
	v_mfma_f32_16x16x32_bf16 v[14:17], v[158:161], v[212:215], v[14:17]
	v_mfma_f32_16x16x32_bf16 v[6:9], v[150:153], v[224:227], v[6:9]
	v_mfma_f32_16x16x32_bf16 v[2:5], v[158:161], v[224:227], v[2:5]
	s_barrier
	s_setprio 0
	s_sleep 1
	s_add_i32 s90, 0, 0x18000
	s_add_i32 s91, 0, 0x1c000
	v_add_u32_e32 v142, s90, v189
	v_add_u32_e32 v158, s91, v189
	ds_read_b128 v[130:133], v142
	ds_read_b128 v[134:137], v142 offset:1024
	ds_read_b128 v[138:141], v142 offset:2048
	ds_read_b128 v[142:145], v142 offset:3072
	ds_read_b128 v[146:149], v158
	ds_read_b128 v[150:153], v158 offset:1024
	ds_read_b128 v[154:157], v158 offset:2048
	ds_read_b128 v[158:161], v158 offset:3072
	s_add_u32 s54, s54, 0x100000
	s_addc_u32 s55, s55, 0
	s_mov_b32 m0, s58
	v_lshl_add_u64 v[232:233], s[54:55], 0, v[184:185]
	ds_read_b128 v[162:165], v210 offset:32768
	ds_read_b128 v[166:169], v210 offset:33792
	ds_read_b128 v[170:173], v210 offset:34816
	ds_read_b128 v[174:177], v210 offset:35840
	ds_read_b128 v[200:203], v210 offset:36864
	ds_read_b128 v[212:215], v210 offset:37888
	ds_read_b128 v[216:219], v210 offset:38912
	ds_read_b128 v[224:227], v210 offset:39936
	global_load_lds_dwordx4 v[232:233], off
	v_lshl_add_u64 v[232:233], s[54:55], 0, v[180:181]
	s_mov_b32 m0, s59
	s_nop 0
	global_load_lds_dwordx4 v[232:233], off
	s_waitcnt vmcnt(8)
	s_waitcnt lgkmcnt(0)
	s_setprio 1
	s_barrier
	v_mfma_f32_16x16x32_bf16 v[126:129], v[130:133], v[162:165], v[126:129]
	v_mfma_f32_16x16x32_bf16 v[122:125], v[138:141], v[162:165], v[122:125]
	v_mfma_f32_16x16x32_bf16 v[110:113], v[130:133], v[170:173], v[110:113]
	v_mfma_f32_16x16x32_bf16 v[106:109], v[138:141], v[170:173], v[106:109]
	v_mfma_f32_16x16x32_bf16 v[94:97], v[130:133], v[200:203], v[94:97]
	v_mfma_f32_16x16x32_bf16 v[90:93], v[138:141], v[200:203], v[90:93]
	v_mfma_f32_16x16x32_bf16 v[78:81], v[130:133], v[216:219], v[78:81]
	v_mfma_f32_16x16x32_bf16 v[74:77], v[138:141], v[216:219], v[74:77]
	v_mfma_f32_16x16x32_bf16 v[126:129], v[134:137], v[166:169], v[126:129]
	v_mfma_f32_16x16x32_bf16 v[122:125], v[142:145], v[166:169], v[122:125]
	v_mfma_f32_16x16x32_bf16 v[110:113], v[134:137], v[174:177], v[110:113]
	v_mfma_f32_16x16x32_bf16 v[106:109], v[142:145], v[174:177], v[106:109]
	v_mfma_f32_16x16x32_bf16 v[94:97], v[134:137], v[212:215], v[94:97]
	v_mfma_f32_16x16x32_bf16 v[90:93], v[142:145], v[212:215], v[90:93]
	v_mfma_f32_16x16x32_bf16 v[78:81], v[134:137], v[224:227], v[78:81]
	v_mfma_f32_16x16x32_bf16 v[74:77], v[142:145], v[224:227], v[74:77]
	v_mfma_f32_16x16x32_bf16 v[118:121], v[146:149], v[162:165], v[118:121]
	v_mfma_f32_16x16x32_bf16 v[114:117], v[154:157], v[162:165], v[114:117]
	v_mfma_f32_16x16x32_bf16 v[102:105], v[146:149], v[170:173], v[102:105]
	v_mfma_f32_16x16x32_bf16 v[98:101], v[154:157], v[170:173], v[98:101]
	v_mfma_f32_16x16x32_bf16 v[86:89], v[146:149], v[200:203], v[86:89]
	v_mfma_f32_16x16x32_bf16 v[82:85], v[154:157], v[200:203], v[82:85]
	v_mfma_f32_16x16x32_bf16 v[70:73], v[146:149], v[216:219], v[70:73]
	v_mfma_f32_16x16x32_bf16 v[66:69], v[154:157], v[216:219], v[66:69]
	v_mfma_f32_16x16x32_bf16 v[118:121], v[150:153], v[166:169], v[118:121]
	v_mfma_f32_16x16x32_bf16 v[114:117], v[158:161], v[166:169], v[114:117]
	v_mfma_f32_16x16x32_bf16 v[102:105], v[150:153], v[174:177], v[102:105]
	v_mfma_f32_16x16x32_bf16 v[98:101], v[158:161], v[174:177], v[98:101]
	v_mfma_f32_16x16x32_bf16 v[86:89], v[150:153], v[212:215], v[86:89]
	v_mfma_f32_16x16x32_bf16 v[82:85], v[158:161], v[212:215], v[82:85]
	v_mfma_f32_16x16x32_bf16 v[70:73], v[150:153], v[224:227], v[70:73]
	v_mfma_f32_16x16x32_bf16 v[66:69], v[158:161], v[224:227], v[66:69]
	s_barrier
	s_setprio 0
	s_sleep 1
	s_add_i32 s54, s90, s31
	v_lshl_add_u64 v[204:205], v[204:205], 0, s[8:9]
	s_mov_b32 m0, s54
	ds_read_b128 v[162:165], v210 offset:49152
	ds_read_b128 v[166:169], v210 offset:50176
	ds_read_b128 v[170:173], v210 offset:51200
	ds_read_b128 v[174:177], v210 offset:52224
	ds_read_b128 v[200:203], v210 offset:53248
	ds_read_b128 v[212:215], v210 offset:54272
	ds_read_b128 v[216:219], v210 offset:55296
	ds_read_b128 v[224:227], v210 offset:56320
	global_load_lds_dwordx4 v[204:205], off
	s_add_i32 m0, s54, 0x2000
	s_add_u32 s52, s52, 0x100080
	v_lshl_add_u64 v[204:205], v[220:221], 0, s[8:9]
	s_addc_u32 s53, s53, 0
	s_add_i32 s54, s91, s31
	global_load_lds_dwordx4 v[204:205], off
	v_lshl_add_u64 v[204:205], s[52:53], 0, v[182:183]
	s_mov_b32 m0, s54
	s_nop 0
	global_load_lds_dwordx4 v[204:205], off
	v_lshl_add_u64 v[204:205], s[52:53], 0, v[178:179]
	s_add_i32 m0, s54, 0x2000
	s_nop 0
	global_load_lds_dwordx4 v[204:205], off
	v_lshl_add_u64 v[204:205], v[228:229], 0, s[8:9]
	s_mov_b32 m0, s62
	s_nop 0
	global_load_lds_dwordx4 v[204:205], off
	v_lshl_add_u64 v[204:205], v[230:231], 0, s[8:9]
	s_mov_b32 m0, s63
	s_nop 0
	global_load_lds_dwordx4 v[204:205], off
	s_waitcnt vmcnt(8)
	s_waitcnt lgkmcnt(0)
	s_setprio 1
	s_barrier
	v_mfma_f32_16x16x32_bf16 v[62:65], v[130:133], v[162:165], v[62:65]
	v_mfma_f32_16x16x32_bf16 v[58:61], v[138:141], v[162:165], v[58:61]
	v_mfma_f32_16x16x32_bf16 v[50:53], v[130:133], v[170:173], v[50:53]
	v_mfma_f32_16x16x32_bf16 v[42:45], v[138:141], v[170:173], v[42:45]
	v_mfma_f32_16x16x32_bf16 v[34:37], v[130:133], v[200:203], v[34:37]
	v_mfma_f32_16x16x32_bf16 v[26:29], v[138:141], v[200:203], v[26:29]
	v_mfma_f32_16x16x32_bf16 v[18:21], v[130:133], v[216:219], v[18:21]
	v_mfma_f32_16x16x32_bf16 v[10:13], v[138:141], v[216:219], v[10:13]
	v_mfma_f32_16x16x32_bf16 v[62:65], v[134:137], v[166:169], v[62:65]
	v_mfma_f32_16x16x32_bf16 v[58:61], v[142:145], v[166:169], v[58:61]
	v_mfma_f32_16x16x32_bf16 v[50:53], v[134:137], v[174:177], v[50:53]
	v_mfma_f32_16x16x32_bf16 v[42:45], v[142:145], v[174:177], v[42:45]
	v_mfma_f32_16x16x32_bf16 v[34:37], v[134:137], v[212:215], v[34:37]
	v_mfma_f32_16x16x32_bf16 v[26:29], v[142:145], v[212:215], v[26:29]
	v_mfma_f32_16x16x32_bf16 v[18:21], v[134:137], v[224:227], v[18:21]
	v_mfma_f32_16x16x32_bf16 v[10:13], v[142:145], v[224:227], v[10:13]
	v_mfma_f32_16x16x32_bf16 v[54:57], v[146:149], v[162:165], v[54:57]
	v_mfma_f32_16x16x32_bf16 v[46:49], v[154:157], v[162:165], v[46:49]
	v_mfma_f32_16x16x32_bf16 v[38:41], v[146:149], v[170:173], v[38:41]
	v_mfma_f32_16x16x32_bf16 v[30:33], v[154:157], v[170:173], v[30:33]
	v_mfma_f32_16x16x32_bf16 v[22:25], v[146:149], v[200:203], v[22:25]
	v_mfma_f32_16x16x32_bf16 v[14:17], v[154:157], v[200:203], v[14:17]
	v_mfma_f32_16x16x32_bf16 v[6:9], v[146:149], v[216:219], v[6:9]
	v_mfma_f32_16x16x32_bf16 v[2:5], v[154:157], v[216:219], v[2:5]
	v_mfma_f32_16x16x32_bf16 v[54:57], v[150:153], v[166:169], v[54:57]
	v_mfma_f32_16x16x32_bf16 v[46:49], v[158:161], v[166:169], v[46:49]
	v_mfma_f32_16x16x32_bf16 v[38:41], v[150:153], v[174:177], v[38:41]
	v_mfma_f32_16x16x32_bf16 v[30:33], v[158:161], v[174:177], v[30:33]
	v_mfma_f32_16x16x32_bf16 v[22:25], v[150:153], v[212:215], v[22:25]
	v_mfma_f32_16x16x32_bf16 v[14:17], v[158:161], v[212:215], v[14:17]
	v_mfma_f32_16x16x32_bf16 v[6:9], v[150:153], v[224:227], v[6:9]
	v_mfma_f32_16x16x32_bf16 v[2:5], v[158:161], v[224:227], v[2:5]
	s_barrier
	s_setprio 0
	s_sleep 1
	s_add_i32 s89, s89, 2
	s_add_u32 s50, s50, 0x100
	s_addc_u32 s51, s51, 0
	s_add_u32 s87, s87, 0x100
	s_addc_u32 s88, s88, 0
	s_cmp_gt_u32 s89, 61
	s_cbranch_scc0 .LBB0_224
	s_and_b64 vcc, exec, s[10:11]
	s_cbranch_vccz .LBB0_229
	s_barrier
	v_lshl_add_u32 v200, s0, 8, v1
	s_cmp_gt_i32 s84, 15
	s_mov_b64 s[50:51], -1
	s_cbranch_scc1 .LBB0_230

.Lpeelb:
	v_add_u32_e32 v142, s51, v220
	v_add_u32_e32 v158, s81, v220
	ds_read_b128 v[130:133], v142
	ds_read_b128 v[134:137], v142 offset:1024
	ds_read_b128 v[138:141], v142 offset:2048
	ds_read_b128 v[142:145], v142 offset:3072
	ds_read_b128 v[146:149], v158
	ds_read_b128 v[150:153], v158 offset:1024
	ds_read_b128 v[154:157], v158 offset:2048
	ds_read_b128 v[158:161], v158 offset:3072
	s_add_u32 s16, s0, 0xfff00080
	s_addc_u32 s17, s1, -1
	s_cmp_eq_u32 s26, 60
	s_cselect_b32 s19, s20, s17
	s_cselect_b32 s18, s21, s16
	s_cselect_b32 s17, s22, s25
	s_cselect_b32 s16, s23, s24
	v_lshl_add_u64 v[218:219], s[0:1], 0, v[194:195]
	s_add_i32 m0, s31, 0xc000
	ds_read_b128 v[162:165], v233
	ds_read_b128 v[166:169], v233 offset:1024
	ds_read_b128 v[170:173], v233 offset:2048
	ds_read_b128 v[174:177], v233 offset:3072
	ds_read_b128 v[202:205], v233 offset:4096
	ds_read_b128 v[206:209], v233 offset:5120
	ds_read_b128 v[210:213], v233 offset:6144
	ds_read_b128 v[214:217], v233 offset:7168
	global_load_lds_dwordx4 v[218:219], off
	v_lshl_add_u64 v[218:219], s[0:1], 0, v[196:197]
	s_add_i32 m0, s31, 0xe000
	s_nop 0
	global_load_lds_dwordx4 v[218:219], off
	s_waitcnt vmcnt(8)
	s_waitcnt lgkmcnt(0)
	s_setprio 1
	s_barrier
	v_mfma_f32_16x16x32_bf16 v[90:93], v[130:133], v[162:165], 0
	v_mfma_f32_16x16x32_bf16 v[58:61], v[138:141], v[162:165], 0
	v_mfma_f32_16x16x32_bf16 v[98:101], v[130:133], v[170:173], 0
	v_mfma_f32_16x16x32_bf16 v[66:69], v[138:141], v[170:173], 0
	v_mfma_f32_16x16x32_bf16 v[102:105], v[130:133], v[202:205], 0
	v_mfma_f32_16x16x32_bf16 v[70:73], v[138:141], v[202:205], 0
	v_mfma_f32_16x16x32_bf16 v[110:113], v[130:133], v[210:213], 0
	v_mfma_f32_16x16x32_bf16 v[78:81], v[138:141], v[210:213], 0
	v_mfma_f32_16x16x32_bf16 v[90:93], v[134:137], v[166:169], v[90:93]
	v_mfma_f32_16x16x32_bf16 v[58:61], v[142:145], v[166:169], v[58:61]
	v_mfma_f32_16x16x32_bf16 v[98:101], v[134:137], v[174:177], v[98:101]
	v_mfma_f32_16x16x32_bf16 v[66:69], v[142:145], v[174:177], v[66:69]
	v_mfma_f32_16x16x32_bf16 v[102:105], v[134:137], v[206:209], v[102:105]
	v_mfma_f32_16x16x32_bf16 v[70:73], v[142:145], v[206:209], v[70:73]
	v_mfma_f32_16x16x32_bf16 v[110:113], v[134:137], v[214:217], v[110:113]
	v_mfma_f32_16x16x32_bf16 v[78:81], v[142:145], v[214:217], v[78:81]
	v_mfma_f32_16x16x32_bf16 v[26:29], v[146:149], v[162:165], 0
	v_mfma_f32_16x16x32_bf16 v[2:5], v[154:157], v[162:165], 0
	v_mfma_f32_16x16x32_bf16 v[34:37], v[146:149], v[170:173], 0
	v_mfma_f32_16x16x32_bf16 v[6:9], v[154:157], v[170:173], 0
	v_mfma_f32_16x16x32_bf16 v[38:41], v[146:149], v[202:205], 0
	v_mfma_f32_16x16x32_bf16 v[10:13], v[154:157], v[202:205], 0
	v_mfma_f32_16x16x32_bf16 v[46:49], v[146:149], v[210:213], 0
	v_mfma_f32_16x16x32_bf16 v[14:17], v[154:157], v[210:213], 0
	v_mfma_f32_16x16x32_bf16 v[26:29], v[150:153], v[166:169], v[26:29]
	v_mfma_f32_16x16x32_bf16 v[2:5], v[158:161], v[166:169], v[2:5]
	v_mfma_f32_16x16x32_bf16 v[34:37], v[150:153], v[174:177], v[34:37]
	v_mfma_f32_16x16x32_bf16 v[6:9], v[158:161], v[174:177], v[6:9]
	v_mfma_f32_16x16x32_bf16 v[38:41], v[150:153], v[206:209], v[38:41]
	v_mfma_f32_16x16x32_bf16 v[10:13], v[158:161], v[206:209], v[10:13]
	v_mfma_f32_16x16x32_bf16 v[46:49], v[150:153], v[214:217], v[46:49]
	v_mfma_f32_16x16x32_bf16 v[14:17], v[158:161], v[214:217], v[14:17]
	s_barrier
	s_setprio 0
	s_sleep 1
	s_add_i32 s27, s51, s15
	v_lshl_add_u64 v[218:219], s[16:17], 0, v[178:179]
	s_mov_b32 m0, s27
	ds_read_b128 v[162:165], v233 offset:16384
	ds_read_b128 v[166:169], v233 offset:17408
	ds_read_b128 v[170:173], v233 offset:18432
	ds_read_b128 v[174:177], v233 offset:19456
	ds_read_b128 v[202:205], v233 offset:20480
	ds_read_b128 v[206:209], v233 offset:21504
	ds_read_b128 v[210:213], v233 offset:22528
	ds_read_b128 v[214:217], v233 offset:23552
	global_load_lds_dwordx4 v[218:219], off
	s_add_i32 m0, s27, 0x2000
	s_add_u32 s62, s16, 0x100000
	v_lshl_add_u64 v[242:243], s[16:17], 0, v[180:181]
	s_addc_u32 s63, s17, 0
	s_add_i32 s27, s81, s15
	global_load_lds_dwordx4 v[242:243], off
	v_lshl_add_u64 v[244:245], s[62:63], 0, v[178:179]
	s_mov_b32 m0, s27
	v_lshl_add_u64 v[246:247], s[18:19], 0, v[180:181]
	global_load_lds_dwordx4 v[244:245], off
	v_lshl_add_u64 v[244:245], s[62:63], 0, v[180:181]
	s_add_i32 m0, s27, 0x2000
	s_nop 0
	global_load_lds_dwordx4 v[244:245], off
	v_lshl_add_u64 v[244:245], s[18:19], 0, v[178:179]
	s_mov_b32 m0, s31
	s_nop 0
	global_load_lds_dwordx4 v[244:245], off
	s_mov_b32 m0, s34
	s_nop 0
	global_load_lds_dwordx4 v[246:247], off
	s_waitcnt vmcnt(8)
	s_waitcnt lgkmcnt(0)
	s_setprio 1
	s_barrier
	v_mfma_f32_16x16x32_bf16 v[114:117], v[130:133], v[162:165], 0
	v_mfma_f32_16x16x32_bf16 v[82:85], v[138:141], v[162:165], 0
	v_mfma_f32_16x16x32_bf16 v[118:121], v[130:133], v[170:173], 0
	v_mfma_f32_16x16x32_bf16 v[86:89], v[138:141], v[170:173], 0
	v_mfma_f32_16x16x32_bf16 v[122:125], v[130:133], v[202:205], 0
	v_mfma_f32_16x16x32_bf16 v[94:97], v[138:141], v[202:205], 0
	v_mfma_f32_16x16x32_bf16 v[126:129], v[130:133], v[210:213], 0
	v_mfma_f32_16x16x32_bf16 v[106:109], v[138:141], v[210:213], 0
	v_mfma_f32_16x16x32_bf16 v[114:117], v[134:137], v[166:169], v[114:117]
	v_mfma_f32_16x16x32_bf16 v[82:85], v[142:145], v[166:169], v[82:85]
	v_mfma_f32_16x16x32_bf16 v[118:121], v[134:137], v[174:177], v[118:121]
	v_mfma_f32_16x16x32_bf16 v[86:89], v[142:145], v[174:177], v[86:89]
	v_mfma_f32_16x16x32_bf16 v[122:125], v[134:137], v[206:209], v[122:125]
	v_mfma_f32_16x16x32_bf16 v[94:97], v[142:145], v[206:209], v[94:97]
	v_mfma_f32_16x16x32_bf16 v[126:129], v[134:137], v[214:217], v[126:129]
	v_mfma_f32_16x16x32_bf16 v[106:109], v[142:145], v[214:217], v[106:109]
	v_mfma_f32_16x16x32_bf16 v[50:53], v[146:149], v[162:165], 0
	v_mfma_f32_16x16x32_bf16 v[18:21], v[154:157], v[162:165], 0
	v_mfma_f32_16x16x32_bf16 v[54:57], v[146:149], v[170:173], 0
	v_mfma_f32_16x16x32_bf16 v[22:25], v[154:157], v[170:173], 0
	v_mfma_f32_16x16x32_bf16 v[62:65], v[146:149], v[202:205], 0
	v_mfma_f32_16x16x32_bf16 v[30:33], v[154:157], v[202:205], 0
	v_mfma_f32_16x16x32_bf16 v[74:77], v[146:149], v[210:213], 0
	v_mfma_f32_16x16x32_bf16 v[42:45], v[154:157], v[210:213], 0
	v_mfma_f32_16x16x32_bf16 v[50:53], v[150:153], v[166:169], v[50:53]
	v_mfma_f32_16x16x32_bf16 v[18:21], v[158:161], v[166:169], v[18:21]
	v_mfma_f32_16x16x32_bf16 v[54:57], v[150:153], v[174:177], v[54:57]
	v_mfma_f32_16x16x32_bf16 v[22:25], v[158:161], v[174:177], v[22:25]
	v_mfma_f32_16x16x32_bf16 v[62:65], v[150:153], v[206:209], v[62:65]
	v_mfma_f32_16x16x32_bf16 v[30:33], v[158:161], v[206:209], v[30:33]
	v_mfma_f32_16x16x32_bf16 v[74:77], v[150:153], v[214:217], v[74:77]
	v_mfma_f32_16x16x32_bf16 v[42:45], v[158:161], v[214:217], v[42:45]
	s_barrier
	s_setprio 0
	s_sleep 1
	s_add_i32 s27, 0, 0x18000
	s_add_i32 s59, 0, 0x1c000
	v_add_u32_e32 v142, s27, v220
	v_add_u32_e32 v158, s59, v220
	ds_read_b128 v[130:133], v142
	ds_read_b128 v[134:137], v142 offset:1024
	ds_read_b128 v[138:141], v142 offset:2048
	ds_read_b128 v[142:145], v142 offset:3072
	ds_read_b128 v[146:149], v158
	ds_read_b128 v[150:153], v158 offset:1024
	ds_read_b128 v[154:157], v158 offset:2048
	ds_read_b128 v[158:161], v158 offset:3072
	s_add_u32 s18, s18, 0x100000
	s_addc_u32 s19, s19, 0
	s_mov_b32 m0, s35
	v_lshl_add_u64 v[248:249], s[18:19], 0, v[178:179]
	ds_read_b128 v[162:165], v233 offset:32768
	ds_read_b128 v[166:169], v233 offset:33792
	ds_read_b128 v[170:173], v233 offset:34816
	ds_read_b128 v[174:177], v233 offset:35840
	ds_read_b128 v[202:205], v233 offset:36864
	ds_read_b128 v[206:209], v233 offset:37888
	ds_read_b128 v[210:213], v233 offset:38912
	ds_read_b128 v[214:217], v233 offset:39936
	global_load_lds_dwordx4 v[248:249], off
	v_lshl_add_u64 v[248:249], s[18:19], 0, v[180:181]
	s_mov_b32 m0, s86
	s_nop 0
	global_load_lds_dwordx4 v[248:249], off
	s_waitcnt vmcnt(8)
	s_waitcnt lgkmcnt(0)
	s_setprio 1
	s_barrier
	v_mfma_f32_16x16x32_bf16 v[90:93], v[130:133], v[162:165], v[90:93]
	v_mfma_f32_16x16x32_bf16 v[58:61], v[138:141], v[162:165], v[58:61]
	v_mfma_f32_16x16x32_bf16 v[98:101], v[130:133], v[170:173], v[98:101]
	v_mfma_f32_16x16x32_bf16 v[66:69], v[138:141], v[170:173], v[66:69]
	v_mfma_f32_16x16x32_bf16 v[102:105], v[130:133], v[202:205], v[102:105]
	v_mfma_f32_16x16x32_bf16 v[70:73], v[138:141], v[202:205], v[70:73]
	v_mfma_f32_16x16x32_bf16 v[110:113], v[130:133], v[210:213], v[110:113]
	v_mfma_f32_16x16x32_bf16 v[78:81], v[138:141], v[210:213], v[78:81]
	v_mfma_f32_16x16x32_bf16 v[90:93], v[134:137], v[166:169], v[90:93]
	v_mfma_f32_16x16x32_bf16 v[58:61], v[142:145], v[166:169], v[58:61]
	v_mfma_f32_16x16x32_bf16 v[98:101], v[134:137], v[174:177], v[98:101]
	v_mfma_f32_16x16x32_bf16 v[66:69], v[142:145], v[174:177], v[66:69]
	v_mfma_f32_16x16x32_bf16 v[102:105], v[134:137], v[206:209], v[102:105]
	v_mfma_f32_16x16x32_bf16 v[70:73], v[142:145], v[206:209], v[70:73]
	v_mfma_f32_16x16x32_bf16 v[110:113], v[134:137], v[214:217], v[110:113]
	v_mfma_f32_16x16x32_bf16 v[78:81], v[142:145], v[214:217], v[78:81]
	v_mfma_f32_16x16x32_bf16 v[26:29], v[146:149], v[162:165], v[26:29]
	v_mfma_f32_16x16x32_bf16 v[2:5], v[154:157], v[162:165], v[2:5]
	v_mfma_f32_16x16x32_bf16 v[34:37], v[146:149], v[170:173], v[34:37]
	v_mfma_f32_16x16x32_bf16 v[6:9], v[154:157], v[170:173], v[6:9]
	v_mfma_f32_16x16x32_bf16 v[38:41], v[146:149], v[202:205], v[38:41]
	v_mfma_f32_16x16x32_bf16 v[10:13], v[154:157], v[202:205], v[10:13]
	v_mfma_f32_16x16x32_bf16 v[46:49], v[146:149], v[210:213], v[46:49]
	v_mfma_f32_16x16x32_bf16 v[14:17], v[154:157], v[210:213], v[14:17]
	v_mfma_f32_16x16x32_bf16 v[26:29], v[150:153], v[166:169], v[26:29]
	v_mfma_f32_16x16x32_bf16 v[2:5], v[158:161], v[166:169], v[2:5]
	v_mfma_f32_16x16x32_bf16 v[34:37], v[150:153], v[174:177], v[34:37]
	v_mfma_f32_16x16x32_bf16 v[6:9], v[158:161], v[174:177], v[6:9]
	v_mfma_f32_16x16x32_bf16 v[38:41], v[150:153], v[206:209], v[38:41]
	v_mfma_f32_16x16x32_bf16 v[10:13], v[158:161], v[206:209], v[10:13]
	v_mfma_f32_16x16x32_bf16 v[46:49], v[150:153], v[214:217], v[46:49]
	v_mfma_f32_16x16x32_bf16 v[14:17], v[158:161], v[214:217], v[14:17]
	s_barrier
	s_setprio 0
	s_sleep 1
	s_add_i32 s18, s27, s15
	v_lshl_add_u64 v[218:219], v[218:219], 0, s[44:45]
	s_mov_b32 m0, s18
	ds_read_b128 v[162:165], v233 offset:49152
	ds_read_b128 v[166:169], v233 offset:50176
	ds_read_b128 v[170:173], v233 offset:51200
	ds_read_b128 v[174:177], v233 offset:52224
	ds_read_b128 v[202:205], v233 offset:53248
	ds_read_b128 v[206:209], v233 offset:54272
	ds_read_b128 v[210:213], v233 offset:55296
	ds_read_b128 v[214:217], v233 offset:56320
	global_load_lds_dwordx4 v[218:219], off
	s_add_i32 m0, s18, 0x2000
	s_add_u32 s16, s16, 0x100080
	v_lshl_add_u64 v[218:219], v[242:243], 0, s[44:45]
	s_addc_u32 s17, s17, 0
	s_add_i32 s18, s59, s15
	global_load_lds_dwordx4 v[218:219], off
	v_lshl_add_u64 v[218:219], s[16:17], 0, v[178:179]
	s_mov_b32 m0, s18
	s_nop 0
	global_load_lds_dwordx4 v[218:219], off
	v_lshl_add_u64 v[218:219], s[16:17], 0, v[180:181]
	s_add_i32 m0, s18, 0x2000
	s_nop 0
	global_load_lds_dwordx4 v[218:219], off
	v_lshl_add_u64 v[218:219], v[244:245], 0, s[44:45]
	s_mov_b32 m0, s66
	s_nop 0
	global_load_lds_dwordx4 v[218:219], off
	v_lshl_add_u64 v[218:219], v[246:247], 0, s[44:45]
	s_mov_b32 m0, s67
	s_nop 0
	global_load_lds_dwordx4 v[218:219], off
	s_waitcnt vmcnt(8)
	s_waitcnt lgkmcnt(0)
	s_setprio 1
	s_barrier
	v_mfma_f32_16x16x32_bf16 v[114:117], v[130:133], v[162:165], v[114:117]
	v_mfma_f32_16x16x32_bf16 v[82:85], v[138:141], v[162:165], v[82:85]
	v_mfma_f32_16x16x32_bf16 v[118:121], v[130:133], v[170:173], v[118:121]
	v_mfma_f32_16x16x32_bf16 v[86:89], v[138:141], v[170:173], v[86:89]
	v_mfma_f32_16x16x32_bf16 v[122:125], v[130:133], v[202:205], v[122:125]
	v_mfma_f32_16x16x32_bf16 v[94:97], v[138:141], v[202:205], v[94:97]
	v_mfma_f32_16x16x32_bf16 v[126:129], v[130:133], v[210:213], v[126:129]
	v_mfma_f32_16x16x32_bf16 v[106:109], v[138:141], v[210:213], v[106:109]
	v_mfma_f32_16x16x32_bf16 v[114:117], v[134:137], v[166:169], v[114:117]
	v_mfma_f32_16x16x32_bf16 v[82:85], v[142:145], v[166:169], v[82:85]
	v_mfma_f32_16x16x32_bf16 v[118:121], v[134:137], v[174:177], v[118:121]
	v_mfma_f32_16x16x32_bf16 v[86:89], v[142:145], v[174:177], v[86:89]
	v_mfma_f32_16x16x32_bf16 v[122:125], v[134:137], v[206:209], v[122:125]
	v_mfma_f32_16x16x32_bf16 v[94:97], v[142:145], v[206:209], v[94:97]
	v_mfma_f32_16x16x32_bf16 v[126:129], v[134:137], v[214:217], v[126:129]
	v_mfma_f32_16x16x32_bf16 v[106:109], v[142:145], v[214:217], v[106:109]
	v_mfma_f32_16x16x32_bf16 v[50:53], v[146:149], v[162:165], v[50:53]
	v_mfma_f32_16x16x32_bf16 v[18:21], v[154:157], v[162:165], v[18:21]
	v_mfma_f32_16x16x32_bf16 v[54:57], v[146:149], v[170:173], v[54:57]
	v_mfma_f32_16x16x32_bf16 v[22:25], v[154:157], v[170:173], v[22:25]
	v_mfma_f32_16x16x32_bf16 v[62:65], v[146:149], v[202:205], v[62:65]
	v_mfma_f32_16x16x32_bf16 v[30:33], v[154:157], v[202:205], v[30:33]
	v_mfma_f32_16x16x32_bf16 v[74:77], v[146:149], v[210:213], v[74:77]
	v_mfma_f32_16x16x32_bf16 v[42:45], v[154:157], v[210:213], v[42:45]
	v_mfma_f32_16x16x32_bf16 v[50:53], v[150:153], v[166:169], v[50:53]
	v_mfma_f32_16x16x32_bf16 v[18:21], v[158:161], v[166:169], v[18:21]
	v_mfma_f32_16x16x32_bf16 v[54:57], v[150:153], v[174:177], v[54:57]
	v_mfma_f32_16x16x32_bf16 v[22:25], v[158:161], v[174:177], v[22:25]
	v_mfma_f32_16x16x32_bf16 v[62:65], v[150:153], v[206:209], v[62:65]
	v_mfma_f32_16x16x32_bf16 v[30:33], v[158:161], v[206:209], v[30:33]
	v_mfma_f32_16x16x32_bf16 v[74:77], v[150:153], v[214:217], v[74:77]
	v_mfma_f32_16x16x32_bf16 v[42:45], v[158:161], v[214:217], v[42:45]
	s_barrier
	s_setprio 0
	s_sleep 1
	s_add_i32 s26, s26, 2
	s_add_u32 s0, s0, 0x100
	s_addc_u32 s1, s1, 0
	s_add_u32 s24, s24, 0x100
	s_addc_u32 s25, s25, 0
.LBB0_672:
	v_add_u32_e32 v142, s51, v220
	v_add_u32_e32 v158, s81, v220
	ds_read_b128 v[130:133], v142
	ds_read_b128 v[134:137], v142 offset:1024
	ds_read_b128 v[138:141], v142 offset:2048
	ds_read_b128 v[142:145], v142 offset:3072
	ds_read_b128 v[146:149], v158
	ds_read_b128 v[150:153], v158 offset:1024
	ds_read_b128 v[154:157], v158 offset:2048
	ds_read_b128 v[158:161], v158 offset:3072
	s_add_u32 s16, s0, 0xfff00080
	s_addc_u32 s17, s1, -1
	s_cmp_eq_u32 s26, 60
	s_cselect_b32 s19, s20, s17
	s_cselect_b32 s18, s21, s16
	s_cselect_b32 s17, s22, s25
	s_cselect_b32 s16, s23, s24
	v_lshl_add_u64 v[218:219], s[0:1], 0, v[194:195]
	s_add_i32 m0, s31, 0xc000
	ds_read_b128 v[162:165], v233
	ds_read_b128 v[166:169], v233 offset:1024
	ds_read_b128 v[170:173], v233 offset:2048
	ds_read_b128 v[174:177], v233 offset:3072
	ds_read_b128 v[202:205], v233 offset:4096
	ds_read_b128 v[206:209], v233 offset:5120
	ds_read_b128 v[210:213], v233 offset:6144
	ds_read_b128 v[214:217], v233 offset:7168
	global_load_lds_dwordx4 v[218:219], off
	v_lshl_add_u64 v[218:219], s[0:1], 0, v[196:197]
	s_add_i32 m0, s31, 0xe000
	s_nop 0
	global_load_lds_dwordx4 v[218:219], off
	s_waitcnt vmcnt(8)
	s_waitcnt lgkmcnt(0)
	s_setprio 1
	s_barrier
	v_mfma_f32_16x16x32_bf16 v[90:93], v[130:133], v[162:165], v[90:93]
	v_mfma_f32_16x16x32_bf16 v[58:61], v[138:141], v[162:165], v[58:61]
	v_mfma_f32_16x16x32_bf16 v[98:101], v[130:133], v[170:173], v[98:101]
	v_mfma_f32_16x16x32_bf16 v[66:69], v[138:141], v[170:173], v[66:69]
	v_mfma_f32_16x16x32_bf16 v[102:105], v[130:133], v[202:205], v[102:105]
	v_mfma_f32_16x16x32_bf16 v[70:73], v[138:141], v[202:205], v[70:73]
	v_mfma_f32_16x16x32_bf16 v[110:113], v[130:133], v[210:213], v[110:113]
	v_mfma_f32_16x16x32_bf16 v[78:81], v[138:141], v[210:213], v[78:81]
	v_mfma_f32_16x16x32_bf16 v[90:93], v[134:137], v[166:169], v[90:93]
	v_mfma_f32_16x16x32_bf16 v[58:61], v[142:145], v[166:169], v[58:61]
	v_mfma_f32_16x16x32_bf16 v[98:101], v[134:137], v[174:177], v[98:101]
	v_mfma_f32_16x16x32_bf16 v[66:69], v[142:145], v[174:177], v[66:69]
	v_mfma_f32_16x16x32_bf16 v[102:105], v[134:137], v[206:209], v[102:105]
	v_mfma_f32_16x16x32_bf16 v[70:73], v[142:145], v[206:209], v[70:73]
	v_mfma_f32_16x16x32_bf16 v[110:113], v[134:137], v[214:217], v[110:113]
	v_mfma_f32_16x16x32_bf16 v[78:81], v[142:145], v[214:217], v[78:81]
	v_mfma_f32_16x16x32_bf16 v[26:29], v[146:149], v[162:165], v[26:29]
	v_mfma_f32_16x16x32_bf16 v[2:5], v[154:157], v[162:165], v[2:5]
	v_mfma_f32_16x16x32_bf16 v[34:37], v[146:149], v[170:173], v[34:37]
	v_mfma_f32_16x16x32_bf16 v[6:9], v[154:157], v[170:173], v[6:9]
	v_mfma_f32_16x16x32_bf16 v[38:41], v[146:149], v[202:205], v[38:41]
	v_mfma_f32_16x16x32_bf16 v[10:13], v[154:157], v[202:205], v[10:13]
	v_mfma_f32_16x16x32_bf16 v[46:49], v[146:149], v[210:213], v[46:49]
	v_mfma_f32_16x16x32_bf16 v[14:17], v[154:157], v[210:213], v[14:17]
	v_mfma_f32_16x16x32_bf16 v[26:29], v[150:153], v[166:169], v[26:29]
	v_mfma_f32_16x16x32_bf16 v[2:5], v[158:161], v[166:169], v[2:5]
	v_mfma_f32_16x16x32_bf16 v[34:37], v[150:153], v[174:177], v[34:37]
	v_mfma_f32_16x16x32_bf16 v[6:9], v[158:161], v[174:177], v[6:9]
	v_mfma_f32_16x16x32_bf16 v[38:41], v[150:153], v[206:209], v[38:41]
	v_mfma_f32_16x16x32_bf16 v[10:13], v[158:161], v[206:209], v[10:13]
	v_mfma_f32_16x16x32_bf16 v[46:49], v[150:153], v[214:217], v[46:49]
	v_mfma_f32_16x16x32_bf16 v[14:17], v[158:161], v[214:217], v[14:17]
	s_barrier
	s_setprio 0
	s_sleep 1
	s_add_i32 s27, s51, s15
	v_lshl_add_u64 v[218:219], s[16:17], 0, v[178:179]
	s_mov_b32 m0, s27
	ds_read_b128 v[162:165], v233 offset:16384
	ds_read_b128 v[166:169], v233 offset:17408
	ds_read_b128 v[170:173], v233 offset:18432
	ds_read_b128 v[174:177], v233 offset:19456
	ds_read_b128 v[202:205], v233 offset:20480
	ds_read_b128 v[206:209], v233 offset:21504
	ds_read_b128 v[210:213], v233 offset:22528
	ds_read_b128 v[214:217], v233 offset:23552
	global_load_lds_dwordx4 v[218:219], off
	s_add_i32 m0, s27, 0x2000
	s_add_u32 s62, s16, 0x100000
	v_lshl_add_u64 v[242:243], s[16:17], 0, v[180:181]
	s_addc_u32 s63, s17, 0
	s_add_i32 s27, s81, s15
	global_load_lds_dwordx4 v[242:243], off
	v_lshl_add_u64 v[244:245], s[62:63], 0, v[178:179]
	s_mov_b32 m0, s27
	v_lshl_add_u64 v[246:247], s[18:19], 0, v[180:181]
	global_load_lds_dwordx4 v[244:245], off
	v_lshl_add_u64 v[244:245], s[62:63], 0, v[180:181]
	s_add_i32 m0, s27, 0x2000
	s_nop 0
	global_load_lds_dwordx4 v[244:245], off
	v_lshl_add_u64 v[244:245], s[18:19], 0, v[178:179]
	s_mov_b32 m0, s31
	s_nop 0
	global_load_lds_dwordx4 v[244:245], off
	s_mov_b32 m0, s34
	s_nop 0
	global_load_lds_dwordx4 v[246:247], off
	s_waitcnt vmcnt(8)
	s_waitcnt lgkmcnt(0)
	s_setprio 1
	s_barrier
	v_mfma_f32_16x16x32_bf16 v[114:117], v[130:133], v[162:165], v[114:117]
	v_mfma_f32_16x16x32_bf16 v[82:85], v[138:141], v[162:165], v[82:85]
	v_mfma_f32_16x16x32_bf16 v[118:121], v[130:133], v[170:173], v[118:121]
	v_mfma_f32_16x16x32_bf16 v[86:89], v[138:141], v[170:173], v[86:89]
	v_mfma_f32_16x16x32_bf16 v[122:125], v[130:133], v[202:205], v[122:125]
	v_mfma_f32_16x16x32_bf16 v[94:97], v[138:141], v[202:205], v[94:97]
	v_mfma_f32_16x16x32_bf16 v[126:129], v[130:133], v[210:213], v[126:129]
	v_mfma_f32_16x16x32_bf16 v[106:109], v[138:141], v[210:213], v[106:109]
	v_mfma_f32_16x16x32_bf16 v[114:117], v[134:137], v[166:169], v[114:117]
	v_mfma_f32_16x16x32_bf16 v[82:85], v[142:145], v[166:169], v[82:85]
	v_mfma_f32_16x16x32_bf16 v[118:121], v[134:137], v[174:177], v[118:121]
	v_mfma_f32_16x16x32_bf16 v[86:89], v[142:145], v[174:177], v[86:89]
	v_mfma_f32_16x16x32_bf16 v[122:125], v[134:137], v[206:209], v[122:125]
	v_mfma_f32_16x16x32_bf16 v[94:97], v[142:145], v[206:209], v[94:97]
	v_mfma_f32_16x16x32_bf16 v[126:129], v[134:137], v[214:217], v[126:129]
	v_mfma_f32_16x16x32_bf16 v[106:109], v[142:145], v[214:217], v[106:109]
	v_mfma_f32_16x16x32_bf16 v[50:53], v[146:149], v[162:165], v[50:53]
	v_mfma_f32_16x16x32_bf16 v[18:21], v[154:157], v[162:165], v[18:21]
	v_mfma_f32_16x16x32_bf16 v[54:57], v[146:149], v[170:173], v[54:57]
	v_mfma_f32_16x16x32_bf16 v[22:25], v[154:157], v[170:173], v[22:25]
	v_mfma_f32_16x16x32_bf16 v[62:65], v[146:149], v[202:205], v[62:65]
	v_mfma_f32_16x16x32_bf16 v[30:33], v[154:157], v[202:205], v[30:33]
	v_mfma_f32_16x16x32_bf16 v[74:77], v[146:149], v[210:213], v[74:77]
	v_mfma_f32_16x16x32_bf16 v[42:45], v[154:157], v[210:213], v[42:45]
	v_mfma_f32_16x16x32_bf16 v[50:53], v[150:153], v[166:169], v[50:53]
	v_mfma_f32_16x16x32_bf16 v[18:21], v[158:161], v[166:169], v[18:21]
	v_mfma_f32_16x16x32_bf16 v[54:57], v[150:153], v[174:177], v[54:57]
	v_mfma_f32_16x16x32_bf16 v[22:25], v[158:161], v[174:177], v[22:25]
	v_mfma_f32_16x16x32_bf16 v[62:65], v[150:153], v[206:209], v[62:65]
	v_mfma_f32_16x16x32_bf16 v[30:33], v[158:161], v[206:209], v[30:33]
	v_mfma_f32_16x16x32_bf16 v[74:77], v[150:153], v[214:217], v[74:77]
	v_mfma_f32_16x16x32_bf16 v[42:45], v[158:161], v[214:217], v[42:45]
	s_barrier
	s_setprio 0
	s_sleep 1
	s_add_i32 s27, 0, 0x18000
	s_add_i32 s59, 0, 0x1c000
	v_add_u32_e32 v142, s27, v220
	v_add_u32_e32 v158, s59, v220
	ds_read_b128 v[130:133], v142
	ds_read_b128 v[134:137], v142 offset:1024
	ds_read_b128 v[138:141], v142 offset:2048
	ds_read_b128 v[142:145], v142 offset:3072
	ds_read_b128 v[146:149], v158
	ds_read_b128 v[150:153], v158 offset:1024
	ds_read_b128 v[154:157], v158 offset:2048
	ds_read_b128 v[158:161], v158 offset:3072
	s_add_u32 s18, s18, 0x100000
	s_addc_u32 s19, s19, 0
	s_mov_b32 m0, s35
	v_lshl_add_u64 v[248:249], s[18:19], 0, v[178:179]
	ds_read_b128 v[162:165], v233 offset:32768
	ds_read_b128 v[166:169], v233 offset:33792
	ds_read_b128 v[170:173], v233 offset:34816
	ds_read_b128 v[174:177], v233 offset:35840
	ds_read_b128 v[202:205], v233 offset:36864
	ds_read_b128 v[206:209], v233 offset:37888
	ds_read_b128 v[210:213], v233 offset:38912
	ds_read_b128 v[214:217], v233 offset:39936
	global_load_lds_dwordx4 v[248:249], off
	v_lshl_add_u64 v[248:249], s[18:19], 0, v[180:181]
	s_mov_b32 m0, s86
	s_nop 0
	global_load_lds_dwordx4 v[248:249], off
	s_waitcnt vmcnt(8)
	s_waitcnt lgkmcnt(0)
	s_setprio 1
	s_barrier
	v_mfma_f32_16x16x32_bf16 v[90:93], v[130:133], v[162:165], v[90:93]
	v_mfma_f32_16x16x32_bf16 v[58:61], v[138:141], v[162:165], v[58:61]
	v_mfma_f32_16x16x32_bf16 v[98:101], v[130:133], v[170:173], v[98:101]
	v_mfma_f32_16x16x32_bf16 v[66:69], v[138:141], v[170:173], v[66:69]
	v_mfma_f32_16x16x32_bf16 v[102:105], v[130:133], v[202:205], v[102:105]
	v_mfma_f32_16x16x32_bf16 v[70:73], v[138:141], v[202:205], v[70:73]
	v_mfma_f32_16x16x32_bf16 v[110:113], v[130:133], v[210:213], v[110:113]
	v_mfma_f32_16x16x32_bf16 v[78:81], v[138:141], v[210:213], v[78:81]
	v_mfma_f32_16x16x32_bf16 v[90:93], v[134:137], v[166:169], v[90:93]
	v_mfma_f32_16x16x32_bf16 v[58:61], v[142:145], v[166:169], v[58:61]
	v_mfma_f32_16x16x32_bf16 v[98:101], v[134:137], v[174:177], v[98:101]
	v_mfma_f32_16x16x32_bf16 v[66:69], v[142:145], v[174:177], v[66:69]
	v_mfma_f32_16x16x32_bf16 v[102:105], v[134:137], v[206:209], v[102:105]
	v_mfma_f32_16x16x32_bf16 v[70:73], v[142:145], v[206:209], v[70:73]
	v_mfma_f32_16x16x32_bf16 v[110:113], v[134:137], v[214:217], v[110:113]
	v_mfma_f32_16x16x32_bf16 v[78:81], v[142:145], v[214:217], v[78:81]
	v_mfma_f32_16x16x32_bf16 v[26:29], v[146:149], v[162:165], v[26:29]
	v_mfma_f32_16x16x32_bf16 v[2:5], v[154:157], v[162:165], v[2:5]
	v_mfma_f32_16x16x32_bf16 v[34:37], v[146:149], v[170:173], v[34:37]
	v_mfma_f32_16x16x32_bf16 v[6:9], v[154:157], v[170:173], v[6:9]
	v_mfma_f32_16x16x32_bf16 v[38:41], v[146:149], v[202:205], v[38:41]
	v_mfma_f32_16x16x32_bf16 v[10:13], v[154:157], v[202:205], v[10:13]
	v_mfma_f32_16x16x32_bf16 v[46:49], v[146:149], v[210:213], v[46:49]
	v_mfma_f32_16x16x32_bf16 v[14:17], v[154:157], v[210:213], v[14:17]
	v_mfma_f32_16x16x32_bf16 v[26:29], v[150:153], v[166:169], v[26:29]
	v_mfma_f32_16x16x32_bf16 v[2:5], v[158:161], v[166:169], v[2:5]
	v_mfma_f32_16x16x32_bf16 v[34:37], v[150:153], v[174:177], v[34:37]
	v_mfma_f32_16x16x32_bf16 v[6:9], v[158:161], v[174:177], v[6:9]
	v_mfma_f32_16x16x32_bf16 v[38:41], v[150:153], v[206:209], v[38:41]
	v_mfma_f32_16x16x32_bf16 v[10:13], v[158:161], v[206:209], v[10:13]
	v_mfma_f32_16x16x32_bf16 v[46:49], v[150:153], v[214:217], v[46:49]
	v_mfma_f32_16x16x32_bf16 v[14:17], v[158:161], v[214:217], v[14:17]
	s_barrier
	s_setprio 0
	s_sleep 1
	s_add_i32 s18, s27, s15
	v_lshl_add_u64 v[218:219], v[218:219], 0, s[44:45]
	s_mov_b32 m0, s18
	ds_read_b128 v[162:165], v233 offset:49152
	ds_read_b128 v[166:169], v233 offset:50176
	ds_read_b128 v[170:173], v233 offset:51200
	ds_read_b128 v[174:177], v233 offset:52224
	ds_read_b128 v[202:205], v233 offset:53248
	ds_read_b128 v[206:209], v233 offset:54272
	ds_read_b128 v[210:213], v233 offset:55296
	ds_read_b128 v[214:217], v233 offset:56320
	global_load_lds_dwordx4 v[218:219], off
	s_add_i32 m0, s18, 0x2000
	s_add_u32 s16, s16, 0x100080
	v_lshl_add_u64 v[218:219], v[242:243], 0, s[44:45]
	s_addc_u32 s17, s17, 0
	s_add_i32 s18, s59, s15
	global_load_lds_dwordx4 v[218:219], off
	v_lshl_add_u64 v[218:219], s[16:17], 0, v[178:179]
	s_mov_b32 m0, s18
	s_nop 0
	global_load_lds_dwordx4 v[218:219], off
	v_lshl_add_u64 v[218:219], s[16:17], 0, v[180:181]
	s_add_i32 m0, s18, 0x2000
	s_nop 0
	global_load_lds_dwordx4 v[218:219], off
	v_lshl_add_u64 v[218:219], v[244:245], 0, s[44:45]
	s_mov_b32 m0, s66
	s_nop 0
	global_load_lds_dwordx4 v[218:219], off
	v_lshl_add_u64 v[218:219], v[246:247], 0, s[44:45]
	s_mov_b32 m0, s67
	s_nop 0
	global_load_lds_dwordx4 v[218:219], off
	s_waitcnt vmcnt(8)
	s_waitcnt lgkmcnt(0)
	s_setprio 1
	s_barrier
	v_mfma_f32_16x16x32_bf16 v[114:117], v[130:133], v[162:165], v[114:117]
	v_mfma_f32_16x16x32_bf16 v[82:85], v[138:141], v[162:165], v[82:85]
	v_mfma_f32_16x16x32_bf16 v[118:121], v[130:133], v[170:173], v[118:121]
	v_mfma_f32_16x16x32_bf16 v[86:89], v[138:141], v[170:173], v[86:89]
	v_mfma_f32_16x16x32_bf16 v[122:125], v[130:133], v[202:205], v[122:125]
	v_mfma_f32_16x16x32_bf16 v[94:97], v[138:141], v[202:205], v[94:97]
	v_mfma_f32_16x16x32_bf16 v[126:129], v[130:133], v[210:213], v[126:129]
	v_mfma_f32_16x16x32_bf16 v[106:109], v[138:141], v[210:213], v[106:109]
	v_mfma_f32_16x16x32_bf16 v[114:117], v[134:137], v[166:169], v[114:117]
	v_mfma_f32_16x16x32_bf16 v[82:85], v[142:145], v[166:169], v[82:85]
	v_mfma_f32_16x16x32_bf16 v[118:121], v[134:137], v[174:177], v[118:121]
	v_mfma_f32_16x16x32_bf16 v[86:89], v[142:145], v[174:177], v[86:89]
	v_mfma_f32_16x16x32_bf16 v[122:125], v[134:137], v[206:209], v[122:125]
	v_mfma_f32_16x16x32_bf16 v[94:97], v[142:145], v[206:209], v[94:97]
	v_mfma_f32_16x16x32_bf16 v[126:129], v[134:137], v[214:217], v[126:129]
	v_mfma_f32_16x16x32_bf16 v[106:109], v[142:145], v[214:217], v[106:109]
	v_mfma_f32_16x16x32_bf16 v[50:53], v[146:149], v[162:165], v[50:53]
	v_mfma_f32_16x16x32_bf16 v[18:21], v[154:157], v[162:165], v[18:21]
	v_mfma_f32_16x16x32_bf16 v[54:57], v[146:149], v[170:173], v[54:57]
	v_mfma_f32_16x16x32_bf16 v[22:25], v[154:157], v[170:173], v[22:25]
	v_mfma_f32_16x16x32_bf16 v[62:65], v[146:149], v[202:205], v[62:65]
	v_mfma_f32_16x16x32_bf16 v[30:33], v[154:157], v[202:205], v[30:33]
	v_mfma_f32_16x16x32_bf16 v[74:77], v[146:149], v[210:213], v[74:77]
	v_mfma_f32_16x16x32_bf16 v[42:45], v[154:157], v[210:213], v[42:45]
	v_mfma_f32_16x16x32_bf16 v[50:53], v[150:153], v[166:169], v[50:53]
	v_mfma_f32_16x16x32_bf16 v[18:21], v[158:161], v[166:169], v[18:21]
	v_mfma_f32_16x16x32_bf16 v[54:57], v[150:153], v[174:177], v[54:57]
	v_mfma_f32_16x16x32_bf16 v[22:25], v[158:161], v[174:177], v[22:25]
	v_mfma_f32_16x16x32_bf16 v[62:65], v[150:153], v[206:209], v[62:65]
	v_mfma_f32_16x16x32_bf16 v[30:33], v[158:161], v[206:209], v[30:33]
	v_mfma_f32_16x16x32_bf16 v[74:77], v[150:153], v[214:217], v[74:77]
	v_mfma_f32_16x16x32_bf16 v[42:45], v[158:161], v[214:217], v[42:45]
	s_barrier
	s_setprio 0
	s_sleep 1
	s_add_i32 s26, s26, 2
	s_add_u32 s0, s0, 0x100
	s_addc_u32 s1, s1, 0
	s_add_u32 s24, s24, 0x100
	s_addc_u32 s25, s25, 0
	s_cmp_gt_u32 s26, 61
	s_cbranch_scc0 .LBB0_672
	s_and_b64 vcc, exec, s[90:91]
	s_cbranch_vccz .LBB0_675
	s_barrier

.Lpeelc:
	ds_read_b128 v[156:159], v153
	ds_read_b128 v[160:163], v153 offset:1024
	ds_read_b128 v[164:167], v153 offset:2048
	ds_read_b128 v[168:171], v153 offset:3072
	ds_read_b128 v[172:175], v154
	ds_read_b128 v[176:179], v154 offset:1024
	ds_read_b128 v[180:183], v154 offset:2048
	ds_read_b128 v[184:187], v154 offset:3072
	s_add_u32 s36, s26, 0xfff00080
	s_addc_u32 s37, s27, -1
	s_cmp_eq_u32 s54, 60
	s_cselect_b32 s39, s19, s37
	s_cselect_b32 s38, s50, s36
	s_cselect_b32 s37, s17, s53
	s_cselect_b32 s36, s51, s52
	v_lshl_add_u64 v[148:149], s[26:27], 0, v[140:141]
	s_add_i32 m0, s25, 0xc000
	ds_read_b128 v[188:191], v155
	ds_read_b128 v[192:195], v155 offset:1024
	ds_read_b128 v[196:199], v155 offset:2048
	ds_read_b128 v[200:203], v155 offset:3072
	ds_read_b128 v[204:207], v155 offset:4096
	ds_read_b128 v[208:211], v155 offset:5120
	ds_read_b128 v[212:215], v155 offset:6144
	ds_read_b128 v[216:219], v155 offset:7168
	global_load_lds_dwordx4 v[148:149], off
	v_lshl_add_u64 v[148:149], s[26:27], 0, v[142:143]
	s_add_i32 m0, s25, 0xe000
	s_nop 0
	global_load_lds_dwordx4 v[148:149], off
	s_waitcnt vmcnt(8)
	s_waitcnt lgkmcnt(0)
	s_setprio 1
	s_barrier
	v_mfma_f32_16x16x32_bf16 v[126:129], v[156:159], v[188:191], 0
	v_mfma_f32_16x16x32_bf16 v[122:125], v[164:167], v[188:191], 0
	v_mfma_f32_16x16x32_bf16 v[118:121], v[156:159], v[196:199], 0
	v_mfma_f32_16x16x32_bf16 v[114:117], v[164:167], v[196:199], 0
	v_mfma_f32_16x16x32_bf16 v[94:97], v[156:159], v[204:207], 0
	v_mfma_f32_16x16x32_bf16 v[90:93], v[164:167], v[204:207], 0
	v_mfma_f32_16x16x32_bf16 v[86:89], v[156:159], v[212:215], 0
	v_mfma_f32_16x16x32_bf16 v[82:85], v[164:167], v[212:215], 0
	v_mfma_f32_16x16x32_bf16 v[126:129], v[160:163], v[192:195], v[126:129]
	v_mfma_f32_16x16x32_bf16 v[122:125], v[168:171], v[192:195], v[122:125]
	v_mfma_f32_16x16x32_bf16 v[118:121], v[160:163], v[200:203], v[118:121]
	v_mfma_f32_16x16x32_bf16 v[114:117], v[168:171], v[200:203], v[114:117]
	v_mfma_f32_16x16x32_bf16 v[94:97], v[160:163], v[208:211], v[94:97]
	v_mfma_f32_16x16x32_bf16 v[90:93], v[168:171], v[208:211], v[90:93]
	v_mfma_f32_16x16x32_bf16 v[86:89], v[160:163], v[216:219], v[86:89]
	v_mfma_f32_16x16x32_bf16 v[82:85], v[168:171], v[216:219], v[82:85]
	v_mfma_f32_16x16x32_bf16 v[110:113], v[172:175], v[188:191], 0
	v_mfma_f32_16x16x32_bf16 v[106:109], v[180:183], v[188:191], 0
	v_mfma_f32_16x16x32_bf16 v[102:105], v[172:175], v[196:199], 0
	v_mfma_f32_16x16x32_bf16 v[98:101], v[180:183], v[196:199], 0
	v_mfma_f32_16x16x32_bf16 v[78:81], v[172:175], v[204:207], 0
	v_mfma_f32_16x16x32_bf16 v[74:77], v[180:183], v[204:207], 0
	v_mfma_f32_16x16x32_bf16 v[70:73], v[172:175], v[212:215], 0
	v_mfma_f32_16x16x32_bf16 v[66:69], v[180:183], v[212:215], 0
	v_mfma_f32_16x16x32_bf16 v[110:113], v[176:179], v[192:195], v[110:113]
	v_mfma_f32_16x16x32_bf16 v[106:109], v[184:187], v[192:195], v[106:109]
	v_mfma_f32_16x16x32_bf16 v[102:105], v[176:179], v[200:203], v[102:105]
	v_mfma_f32_16x16x32_bf16 v[98:101], v[184:187], v[200:203], v[98:101]
	v_mfma_f32_16x16x32_bf16 v[78:81], v[176:179], v[208:211], v[78:81]
	v_mfma_f32_16x16x32_bf16 v[74:77], v[184:187], v[208:211], v[74:77]
	v_mfma_f32_16x16x32_bf16 v[70:73], v[176:179], v[216:219], v[70:73]
	v_mfma_f32_16x16x32_bf16 v[66:69], v[184:187], v[216:219], v[66:69]
	s_barrier
	s_setprio 0
	s_sleep 1
	s_add_i32 s55, s44, s13
	v_lshl_add_u64 v[148:149], s[36:37], 0, v[134:135]
	s_mov_b32 m0, s55
	ds_read_b128 v[188:191], v155 offset:16384
	ds_read_b128 v[192:195], v155 offset:17408
	ds_read_b128 v[196:199], v155 offset:18432
	ds_read_b128 v[200:203], v155 offset:19456
	ds_read_b128 v[204:207], v155 offset:20480
	ds_read_b128 v[208:211], v155 offset:21504
	ds_read_b128 v[212:215], v155 offset:22528
	ds_read_b128 v[216:219], v155 offset:23552
	global_load_lds_dwordx4 v[148:149], off
	s_add_i32 m0, s55, 0x2000
	s_add_u32 s56, s36, 0x100000
	v_lshl_add_u64 v[220:221], s[36:37], 0, v[130:131]
	s_addc_u32 s57, s37, 0
	s_add_i32 s55, s45, s13
	global_load_lds_dwordx4 v[220:221], off
	v_lshl_add_u64 v[224:225], s[56:57], 0, v[134:135]
	s_mov_b32 m0, s55
	v_lshl_add_u64 v[226:227], s[38:39], 0, v[132:133]
	global_load_lds_dwordx4 v[224:225], off
	v_lshl_add_u64 v[224:225], s[56:57], 0, v[130:131]
	s_add_i32 m0, s55, 0x2000
	s_nop 0
	global_load_lds_dwordx4 v[224:225], off
	v_lshl_add_u64 v[224:225], s[38:39], 0, v[136:137]
	s_mov_b32 m0, s25
	s_nop 0
	global_load_lds_dwordx4 v[224:225], off
	s_mov_b32 m0, s31
	s_nop 0
	global_load_lds_dwordx4 v[226:227], off
	s_waitcnt vmcnt(8)
	s_waitcnt lgkmcnt(0)
	s_setprio 1
	s_barrier
	v_mfma_f32_16x16x32_bf16 v[62:65], v[156:159], v[188:191], 0
	v_mfma_f32_16x16x32_bf16 v[58:61], v[164:167], v[188:191], 0
	v_mfma_f32_16x16x32_bf16 v[54:57], v[156:159], v[196:199], 0
	v_mfma_f32_16x16x32_bf16 v[50:53], v[164:167], v[196:199], 0
	v_mfma_f32_16x16x32_bf16 v[30:33], v[156:159], v[204:207], 0
	v_mfma_f32_16x16x32_bf16 v[26:29], v[164:167], v[204:207], 0
	v_mfma_f32_16x16x32_bf16 v[22:25], v[156:159], v[212:215], 0
	v_mfma_f32_16x16x32_bf16 v[18:21], v[164:167], v[212:215], 0
	v_mfma_f32_16x16x32_bf16 v[62:65], v[160:163], v[192:195], v[62:65]
	v_mfma_f32_16x16x32_bf16 v[58:61], v[168:171], v[192:195], v[58:61]
	v_mfma_f32_16x16x32_bf16 v[54:57], v[160:163], v[200:203], v[54:57]
	v_mfma_f32_16x16x32_bf16 v[50:53], v[168:171], v[200:203], v[50:53]
	v_mfma_f32_16x16x32_bf16 v[30:33], v[160:163], v[208:211], v[30:33]
	v_mfma_f32_16x16x32_bf16 v[26:29], v[168:171], v[208:211], v[26:29]
	v_mfma_f32_16x16x32_bf16 v[22:25], v[160:163], v[216:219], v[22:25]
	v_mfma_f32_16x16x32_bf16 v[18:21], v[168:171], v[216:219], v[18:21]
	v_mfma_f32_16x16x32_bf16 v[46:49], v[172:175], v[188:191], 0
	v_mfma_f32_16x16x32_bf16 v[42:45], v[180:183], v[188:191], 0
	v_mfma_f32_16x16x32_bf16 v[38:41], v[172:175], v[196:199], 0
	v_mfma_f32_16x16x32_bf16 v[34:37], v[180:183], v[196:199], 0
	v_mfma_f32_16x16x32_bf16 v[14:17], v[172:175], v[204:207], 0
	v_mfma_f32_16x16x32_bf16 v[10:13], v[180:183], v[204:207], 0
	v_mfma_f32_16x16x32_bf16 v[6:9], v[172:175], v[212:215], 0
	v_mfma_f32_16x16x32_bf16 v[2:5], v[180:183], v[212:215], 0
	v_mfma_f32_16x16x32_bf16 v[46:49], v[176:179], v[192:195], v[46:49]
	v_mfma_f32_16x16x32_bf16 v[42:45], v[184:187], v[192:195], v[42:45]
	v_mfma_f32_16x16x32_bf16 v[38:41], v[176:179], v[200:203], v[38:41]
	v_mfma_f32_16x16x32_bf16 v[34:37], v[184:187], v[200:203], v[34:37]
	v_mfma_f32_16x16x32_bf16 v[14:17], v[176:179], v[208:211], v[14:17]
	v_mfma_f32_16x16x32_bf16 v[10:13], v[184:187], v[208:211], v[10:13]
	v_mfma_f32_16x16x32_bf16 v[6:9], v[176:179], v[216:219], v[6:9]
	v_mfma_f32_16x16x32_bf16 v[2:5], v[184:187], v[216:219], v[2:5]
	s_barrier
	s_setprio 0
	s_sleep 1
	s_add_i32 s55, 0, 0x18000
	s_add_i32 s56, 0, 0x1c000
	v_add_u32_e32 v168, s55, v151
	v_add_u32_e32 v184, s56, v151
	ds_read_b128 v[156:159], v168
	ds_read_b128 v[160:163], v168 offset:1024
	ds_read_b128 v[164:167], v168 offset:2048
	ds_read_b128 v[168:171], v168 offset:3072
	ds_read_b128 v[172:175], v184
	ds_read_b128 v[176:179], v184 offset:1024
	ds_read_b128 v[180:183], v184 offset:2048
	ds_read_b128 v[184:187], v184 offset:3072
	s_add_u32 s38, s38, 0x100000
	s_addc_u32 s39, s39, 0
	s_mov_b32 m0, s34
	v_lshl_add_u64 v[228:229], s[38:39], 0, v[136:137]
	ds_read_b128 v[188:191], v155 offset:32768
	ds_read_b128 v[192:195], v155 offset:33792
	ds_read_b128 v[196:199], v155 offset:34816
	ds_read_b128 v[200:203], v155 offset:35840
	ds_read_b128 v[204:207], v155 offset:36864
	ds_read_b128 v[208:211], v155 offset:37888
	ds_read_b128 v[212:215], v155 offset:38912
	ds_read_b128 v[216:219], v155 offset:39936
	global_load_lds_dwordx4 v[228:229], off
	v_lshl_add_u64 v[228:229], s[38:39], 0, v[132:133]
	s_mov_b32 m0, s35
	s_nop 0
	global_load_lds_dwordx4 v[228:229], off
	s_waitcnt vmcnt(8)
	s_waitcnt lgkmcnt(0)
	s_setprio 1
	s_barrier
	v_mfma_f32_16x16x32_bf16 v[126:129], v[156:159], v[188:191], v[126:129]
	v_mfma_f32_16x16x32_bf16 v[122:125], v[164:167], v[188:191], v[122:125]
	v_mfma_f32_16x16x32_bf16 v[118:121], v[156:159], v[196:199], v[118:121]
	v_mfma_f32_16x16x32_bf16 v[114:117], v[164:167], v[196:199], v[114:117]
	v_mfma_f32_16x16x32_bf16 v[94:97], v[156:159], v[204:207], v[94:97]
	v_mfma_f32_16x16x32_bf16 v[90:93], v[164:167], v[204:207], v[90:93]
	v_mfma_f32_16x16x32_bf16 v[86:89], v[156:159], v[212:215], v[86:89]
	v_mfma_f32_16x16x32_bf16 v[82:85], v[164:167], v[212:215], v[82:85]
	v_mfma_f32_16x16x32_bf16 v[126:129], v[160:163], v[192:195], v[126:129]
	v_mfma_f32_16x16x32_bf16 v[122:125], v[168:171], v[192:195], v[122:125]
	v_mfma_f32_16x16x32_bf16 v[118:121], v[160:163], v[200:203], v[118:121]
	v_mfma_f32_16x16x32_bf16 v[114:117], v[168:171], v[200:203], v[114:117]
	v_mfma_f32_16x16x32_bf16 v[94:97], v[160:163], v[208:211], v[94:97]
	v_mfma_f32_16x16x32_bf16 v[90:93], v[168:171], v[208:211], v[90:93]
	v_mfma_f32_16x16x32_bf16 v[86:89], v[160:163], v[216:219], v[86:89]
	v_mfma_f32_16x16x32_bf16 v[82:85], v[168:171], v[216:219], v[82:85]
	v_mfma_f32_16x16x32_bf16 v[110:113], v[172:175], v[188:191], v[110:113]
	v_mfma_f32_16x16x32_bf16 v[106:109], v[180:183], v[188:191], v[106:109]
	v_mfma_f32_16x16x32_bf16 v[102:105], v[172:175], v[196:199], v[102:105]
	v_mfma_f32_16x16x32_bf16 v[98:101], v[180:183], v[196:199], v[98:101]
	v_mfma_f32_16x16x32_bf16 v[78:81], v[172:175], v[204:207], v[78:81]
	v_mfma_f32_16x16x32_bf16 v[74:77], v[180:183], v[204:207], v[74:77]
	v_mfma_f32_16x16x32_bf16 v[70:73], v[172:175], v[212:215], v[70:73]
	v_mfma_f32_16x16x32_bf16 v[66:69], v[180:183], v[212:215], v[66:69]
	v_mfma_f32_16x16x32_bf16 v[110:113], v[176:179], v[192:195], v[110:113]
	v_mfma_f32_16x16x32_bf16 v[106:109], v[184:187], v[192:195], v[106:109]
	v_mfma_f32_16x16x32_bf16 v[102:105], v[176:179], v[200:203], v[102:105]
	v_mfma_f32_16x16x32_bf16 v[98:101], v[184:187], v[200:203], v[98:101]
	v_mfma_f32_16x16x32_bf16 v[78:81], v[176:179], v[208:211], v[78:81]
	v_mfma_f32_16x16x32_bf16 v[74:77], v[184:187], v[208:211], v[74:77]
	v_mfma_f32_16x16x32_bf16 v[70:73], v[176:179], v[216:219], v[70:73]
	v_mfma_f32_16x16x32_bf16 v[66:69], v[184:187], v[216:219], v[66:69]
	s_barrier
	s_setprio 0
	s_sleep 1
	s_add_i32 s38, s55, s13
	v_lshl_add_u64 v[148:149], v[148:149], 0, s[6:7]
	s_mov_b32 m0, s38
	ds_read_b128 v[188:191], v155 offset:49152
	ds_read_b128 v[192:195], v155 offset:50176
	ds_read_b128 v[196:199], v155 offset:51200
	ds_read_b128 v[200:203], v155 offset:52224
	ds_read_b128 v[204:207], v155 offset:53248
	ds_read_b128 v[208:211], v155 offset:54272
	ds_read_b128 v[212:215], v155 offset:55296
	ds_read_b128 v[216:219], v155 offset:56320
	global_load_lds_dwordx4 v[148:149], off
	s_add_i32 m0, s38, 0x2000
	s_add_u32 s36, s36, 0x100080
	v_lshl_add_u64 v[148:149], v[220:221], 0, s[6:7]
	s_addc_u32 s37, s37, 0
	s_add_i32 s38, s56, s13
	global_load_lds_dwordx4 v[148:149], off
	v_lshl_add_u64 v[148:149], s[36:37], 0, v[134:135]
	s_mov_b32 m0, s38
	s_nop 0
	global_load_lds_dwordx4 v[148:149], off
	v_lshl_add_u64 v[148:149], s[36:37], 0, v[130:131]
	s_add_i32 m0, s38, 0x2000
	s_nop 0
	global_load_lds_dwordx4 v[148:149], off
	v_lshl_add_u64 v[148:149], v[224:225], 0, s[6:7]
	s_mov_b32 m0, s41
	s_nop 0
	global_load_lds_dwordx4 v[148:149], off
	v_lshl_add_u64 v[148:149], v[226:227], 0, s[6:7]
	s_mov_b32 m0, s42
	s_nop 0
	global_load_lds_dwordx4 v[148:149], off
	s_waitcnt vmcnt(8)
	s_waitcnt lgkmcnt(0)
	s_setprio 1
	s_barrier
	v_mfma_f32_16x16x32_bf16 v[62:65], v[156:159], v[188:191], v[62:65]
	v_mfma_f32_16x16x32_bf16 v[58:61], v[164:167], v[188:191], v[58:61]
	v_mfma_f32_16x16x32_bf16 v[54:57], v[156:159], v[196:199], v[54:57]
	v_mfma_f32_16x16x32_bf16 v[50:53], v[164:167], v[196:199], v[50:53]
	v_mfma_f32_16x16x32_bf16 v[30:33], v[156:159], v[204:207], v[30:33]
	v_mfma_f32_16x16x32_bf16 v[26:29], v[164:167], v[204:207], v[26:29]
	v_mfma_f32_16x16x32_bf16 v[22:25], v[156:159], v[212:215], v[22:25]
	v_mfma_f32_16x16x32_bf16 v[18:21], v[164:167], v[212:215], v[18:21]
	v_mfma_f32_16x16x32_bf16 v[62:65], v[160:163], v[192:195], v[62:65]
	v_mfma_f32_16x16x32_bf16 v[58:61], v[168:171], v[192:195], v[58:61]
	v_mfma_f32_16x16x32_bf16 v[54:57], v[160:163], v[200:203], v[54:57]
	v_mfma_f32_16x16x32_bf16 v[50:53], v[168:171], v[200:203], v[50:53]
	v_mfma_f32_16x16x32_bf16 v[30:33], v[160:163], v[208:211], v[30:33]
	v_mfma_f32_16x16x32_bf16 v[26:29], v[168:171], v[208:211], v[26:29]
	v_mfma_f32_16x16x32_bf16 v[22:25], v[160:163], v[216:219], v[22:25]
	v_mfma_f32_16x16x32_bf16 v[18:21], v[168:171], v[216:219], v[18:21]
	v_mfma_f32_16x16x32_bf16 v[46:49], v[172:175], v[188:191], v[46:49]
	v_mfma_f32_16x16x32_bf16 v[42:45], v[180:183], v[188:191], v[42:45]
	v_mfma_f32_16x16x32_bf16 v[38:41], v[172:175], v[196:199], v[38:41]
	v_mfma_f32_16x16x32_bf16 v[34:37], v[180:183], v[196:199], v[34:37]
	v_mfma_f32_16x16x32_bf16 v[14:17], v[172:175], v[204:207], v[14:17]
	v_mfma_f32_16x16x32_bf16 v[10:13], v[180:183], v[204:207], v[10:13]
	v_mfma_f32_16x16x32_bf16 v[6:9], v[172:175], v[212:215], v[6:9]
	v_mfma_f32_16x16x32_bf16 v[2:5], v[180:183], v[212:215], v[2:5]
	v_mfma_f32_16x16x32_bf16 v[46:49], v[176:179], v[192:195], v[46:49]
	v_mfma_f32_16x16x32_bf16 v[42:45], v[184:187], v[192:195], v[42:45]
	v_mfma_f32_16x16x32_bf16 v[38:41], v[176:179], v[200:203], v[38:41]
	v_mfma_f32_16x16x32_bf16 v[34:37], v[184:187], v[200:203], v[34:37]
	v_mfma_f32_16x16x32_bf16 v[14:17], v[176:179], v[208:211], v[14:17]
	v_mfma_f32_16x16x32_bf16 v[10:13], v[184:187], v[208:211], v[10:13]
	v_mfma_f32_16x16x32_bf16 v[6:9], v[176:179], v[216:219], v[6:9]
	v_mfma_f32_16x16x32_bf16 v[2:5], v[184:187], v[216:219], v[2:5]
	s_barrier
	s_setprio 0
	s_sleep 1
	s_add_i32 s54, s54, 2
	s_add_u32 s26, s26, 0x100
	s_addc_u32 s27, s27, 0
	s_add_u32 s52, s52, 0x100
	s_addc_u32 s53, s53, 0
.LBB0_788:
	ds_read_b128 v[156:159], v153
	ds_read_b128 v[160:163], v153 offset:1024
	ds_read_b128 v[164:167], v153 offset:2048
	ds_read_b128 v[168:171], v153 offset:3072
	ds_read_b128 v[172:175], v154
	ds_read_b128 v[176:179], v154 offset:1024
	ds_read_b128 v[180:183], v154 offset:2048
	ds_read_b128 v[184:187], v154 offset:3072
	s_add_u32 s36, s26, 0xfff00080
	s_addc_u32 s37, s27, -1
	s_cmp_eq_u32 s54, 60
	s_cselect_b32 s39, s19, s37
	s_cselect_b32 s38, s50, s36
	s_cselect_b32 s37, s17, s53
	s_cselect_b32 s36, s51, s52
	v_lshl_add_u64 v[148:149], s[26:27], 0, v[140:141]
	s_add_i32 m0, s25, 0xc000
	ds_read_b128 v[188:191], v155
	ds_read_b128 v[192:195], v155 offset:1024
	ds_read_b128 v[196:199], v155 offset:2048
	ds_read_b128 v[200:203], v155 offset:3072
	ds_read_b128 v[204:207], v155 offset:4096
	ds_read_b128 v[208:211], v155 offset:5120
	ds_read_b128 v[212:215], v155 offset:6144
	ds_read_b128 v[216:219], v155 offset:7168
	global_load_lds_dwordx4 v[148:149], off
	v_lshl_add_u64 v[148:149], s[26:27], 0, v[142:143]
	s_add_i32 m0, s25, 0xe000
	s_nop 0
	global_load_lds_dwordx4 v[148:149], off
	s_waitcnt vmcnt(8)
	s_waitcnt lgkmcnt(0)
	s_setprio 1
	s_barrier
	v_mfma_f32_16x16x32_bf16 v[126:129], v[156:159], v[188:191], v[126:129]
	v_mfma_f32_16x16x32_bf16 v[122:125], v[164:167], v[188:191], v[122:125]
	v_mfma_f32_16x16x32_bf16 v[118:121], v[156:159], v[196:199], v[118:121]
	v_mfma_f32_16x16x32_bf16 v[114:117], v[164:167], v[196:199], v[114:117]
	v_mfma_f32_16x16x32_bf16 v[94:97], v[156:159], v[204:207], v[94:97]
	v_mfma_f32_16x16x32_bf16 v[90:93], v[164:167], v[204:207], v[90:93]
	v_mfma_f32_16x16x32_bf16 v[86:89], v[156:159], v[212:215], v[86:89]
	v_mfma_f32_16x16x32_bf16 v[82:85], v[164:167], v[212:215], v[82:85]
	v_mfma_f32_16x16x32_bf16 v[126:129], v[160:163], v[192:195], v[126:129]
	v_mfma_f32_16x16x32_bf16 v[122:125], v[168:171], v[192:195], v[122:125]
	v_mfma_f32_16x16x32_bf16 v[118:121], v[160:163], v[200:203], v[118:121]
	v_mfma_f32_16x16x32_bf16 v[114:117], v[168:171], v[200:203], v[114:117]
	v_mfma_f32_16x16x32_bf16 v[94:97], v[160:163], v[208:211], v[94:97]
	v_mfma_f32_16x16x32_bf16 v[90:93], v[168:171], v[208:211], v[90:93]
	v_mfma_f32_16x16x32_bf16 v[86:89], v[160:163], v[216:219], v[86:89]
	v_mfma_f32_16x16x32_bf16 v[82:85], v[168:171], v[216:219], v[82:85]
	v_mfma_f32_16x16x32_bf16 v[110:113], v[172:175], v[188:191], v[110:113]
	v_mfma_f32_16x16x32_bf16 v[106:109], v[180:183], v[188:191], v[106:109]
	v_mfma_f32_16x16x32_bf16 v[102:105], v[172:175], v[196:199], v[102:105]
	v_mfma_f32_16x16x32_bf16 v[98:101], v[180:183], v[196:199], v[98:101]
	v_mfma_f32_16x16x32_bf16 v[78:81], v[172:175], v[204:207], v[78:81]
	v_mfma_f32_16x16x32_bf16 v[74:77], v[180:183], v[204:207], v[74:77]
	v_mfma_f32_16x16x32_bf16 v[70:73], v[172:175], v[212:215], v[70:73]
	v_mfma_f32_16x16x32_bf16 v[66:69], v[180:183], v[212:215], v[66:69]
	v_mfma_f32_16x16x32_bf16 v[110:113], v[176:179], v[192:195], v[110:113]
	v_mfma_f32_16x16x32_bf16 v[106:109], v[184:187], v[192:195], v[106:109]
	v_mfma_f32_16x16x32_bf16 v[102:105], v[176:179], v[200:203], v[102:105]
	v_mfma_f32_16x16x32_bf16 v[98:101], v[184:187], v[200:203], v[98:101]
	v_mfma_f32_16x16x32_bf16 v[78:81], v[176:179], v[208:211], v[78:81]
	v_mfma_f32_16x16x32_bf16 v[74:77], v[184:187], v[208:211], v[74:77]
	v_mfma_f32_16x16x32_bf16 v[70:73], v[176:179], v[216:219], v[70:73]
	v_mfma_f32_16x16x32_bf16 v[66:69], v[184:187], v[216:219], v[66:69]
	s_barrier
	s_setprio 0
	s_sleep 1
	s_add_i32 s55, s44, s13
	v_lshl_add_u64 v[148:149], s[36:37], 0, v[134:135]
	s_mov_b32 m0, s55
	ds_read_b128 v[188:191], v155 offset:16384
	ds_read_b128 v[192:195], v155 offset:17408
	ds_read_b128 v[196:199], v155 offset:18432
	ds_read_b128 v[200:203], v155 offset:19456
	ds_read_b128 v[204:207], v155 offset:20480
	ds_read_b128 v[208:211], v155 offset:21504
	ds_read_b128 v[212:215], v155 offset:22528
	ds_read_b128 v[216:219], v155 offset:23552
	global_load_lds_dwordx4 v[148:149], off
	s_add_i32 m0, s55, 0x2000
	s_add_u32 s56, s36, 0x100000
	v_lshl_add_u64 v[220:221], s[36:37], 0, v[130:131]
	s_addc_u32 s57, s37, 0
	s_add_i32 s55, s45, s13
	global_load_lds_dwordx4 v[220:221], off
	v_lshl_add_u64 v[224:225], s[56:57], 0, v[134:135]
	s_mov_b32 m0, s55
	v_lshl_add_u64 v[226:227], s[38:39], 0, v[132:133]
	global_load_lds_dwordx4 v[224:225], off
	v_lshl_add_u64 v[224:225], s[56:57], 0, v[130:131]
	s_add_i32 m0, s55, 0x2000
	s_nop 0
	global_load_lds_dwordx4 v[224:225], off
	v_lshl_add_u64 v[224:225], s[38:39], 0, v[136:137]
	s_mov_b32 m0, s25
	s_nop 0
	global_load_lds_dwordx4 v[224:225], off
	s_mov_b32 m0, s31
	s_nop 0
	global_load_lds_dwordx4 v[226:227], off
	s_waitcnt vmcnt(8)
	s_waitcnt lgkmcnt(0)
	s_setprio 1
	s_barrier
	v_mfma_f32_16x16x32_bf16 v[62:65], v[156:159], v[188:191], v[62:65]
	v_mfma_f32_16x16x32_bf16 v[58:61], v[164:167], v[188:191], v[58:61]
	v_mfma_f32_16x16x32_bf16 v[54:57], v[156:159], v[196:199], v[54:57]
	v_mfma_f32_16x16x32_bf16 v[50:53], v[164:167], v[196:199], v[50:53]
	v_mfma_f32_16x16x32_bf16 v[30:33], v[156:159], v[204:207], v[30:33]
	v_mfma_f32_16x16x32_bf16 v[26:29], v[164:167], v[204:207], v[26:29]
	v_mfma_f32_16x16x32_bf16 v[22:25], v[156:159], v[212:215], v[22:25]
	v_mfma_f32_16x16x32_bf16 v[18:21], v[164:167], v[212:215], v[18:21]
	v_mfma_f32_16x16x32_bf16 v[62:65], v[160:163], v[192:195], v[62:65]
	v_mfma_f32_16x16x32_bf16 v[58:61], v[168:171], v[192:195], v[58:61]
	v_mfma_f32_16x16x32_bf16 v[54:57], v[160:163], v[200:203], v[54:57]
	v_mfma_f32_16x16x32_bf16 v[50:53], v[168:171], v[200:203], v[50:53]
	v_mfma_f32_16x16x32_bf16 v[30:33], v[160:163], v[208:211], v[30:33]
	v_mfma_f32_16x16x32_bf16 v[26:29], v[168:171], v[208:211], v[26:29]
	v_mfma_f32_16x16x32_bf16 v[22:25], v[160:163], v[216:219], v[22:25]
	v_mfma_f32_16x16x32_bf16 v[18:21], v[168:171], v[216:219], v[18:21]
	v_mfma_f32_16x16x32_bf16 v[46:49], v[172:175], v[188:191], v[46:49]
	v_mfma_f32_16x16x32_bf16 v[42:45], v[180:183], v[188:191], v[42:45]
	v_mfma_f32_16x16x32_bf16 v[38:41], v[172:175], v[196:199], v[38:41]
	v_mfma_f32_16x16x32_bf16 v[34:37], v[180:183], v[196:199], v[34:37]
	v_mfma_f32_16x16x32_bf16 v[14:17], v[172:175], v[204:207], v[14:17]
	v_mfma_f32_16x16x32_bf16 v[10:13], v[180:183], v[204:207], v[10:13]
	v_mfma_f32_16x16x32_bf16 v[6:9], v[172:175], v[212:215], v[6:9]
	v_mfma_f32_16x16x32_bf16 v[2:5], v[180:183], v[212:215], v[2:5]
	v_mfma_f32_16x16x32_bf16 v[46:49], v[176:179], v[192:195], v[46:49]
	v_mfma_f32_16x16x32_bf16 v[42:45], v[184:187], v[192:195], v[42:45]
	v_mfma_f32_16x16x32_bf16 v[38:41], v[176:179], v[200:203], v[38:41]
	v_mfma_f32_16x16x32_bf16 v[34:37], v[184:187], v[200:203], v[34:37]
	v_mfma_f32_16x16x32_bf16 v[14:17], v[176:179], v[208:211], v[14:17]
	v_mfma_f32_16x16x32_bf16 v[10:13], v[184:187], v[208:211], v[10:13]
	v_mfma_f32_16x16x32_bf16 v[6:9], v[176:179], v[216:219], v[6:9]
	v_mfma_f32_16x16x32_bf16 v[2:5], v[184:187], v[216:219], v[2:5]
	s_barrier
	s_setprio 0
	s_sleep 1
	s_add_i32 s55, 0, 0x18000
	s_add_i32 s56, 0, 0x1c000
	v_add_u32_e32 v168, s55, v151
	v_add_u32_e32 v184, s56, v151
	ds_read_b128 v[156:159], v168
	ds_read_b128 v[160:163], v168 offset:1024
	ds_read_b128 v[164:167], v168 offset:2048
	ds_read_b128 v[168:171], v168 offset:3072
	ds_read_b128 v[172:175], v184
	ds_read_b128 v[176:179], v184 offset:1024
	ds_read_b128 v[180:183], v184 offset:2048
	ds_read_b128 v[184:187], v184 offset:3072
	s_add_u32 s38, s38, 0x100000
	s_addc_u32 s39, s39, 0
	s_mov_b32 m0, s34
	v_lshl_add_u64 v[228:229], s[38:39], 0, v[136:137]
	ds_read_b128 v[188:191], v155 offset:32768
	ds_read_b128 v[192:195], v155 offset:33792
	ds_read_b128 v[196:199], v155 offset:34816
	ds_read_b128 v[200:203], v155 offset:35840
	ds_read_b128 v[204:207], v155 offset:36864
	ds_read_b128 v[208:211], v155 offset:37888
	ds_read_b128 v[212:215], v155 offset:38912
	ds_read_b128 v[216:219], v155 offset:39936
	global_load_lds_dwordx4 v[228:229], off
	v_lshl_add_u64 v[228:229], s[38:39], 0, v[132:133]
	s_mov_b32 m0, s35
	s_nop 0
	global_load_lds_dwordx4 v[228:229], off
	s_waitcnt vmcnt(8)
	s_waitcnt lgkmcnt(0)
	s_setprio 1
	s_barrier
	v_mfma_f32_16x16x32_bf16 v[126:129], v[156:159], v[188:191], v[126:129]
	v_mfma_f32_16x16x32_bf16 v[122:125], v[164:167], v[188:191], v[122:125]
	v_mfma_f32_16x16x32_bf16 v[118:121], v[156:159], v[196:199], v[118:121]
	v_mfma_f32_16x16x32_bf16 v[114:117], v[164:167], v[196:199], v[114:117]
	v_mfma_f32_16x16x32_bf16 v[94:97], v[156:159], v[204:207], v[94:97]
	v_mfma_f32_16x16x32_bf16 v[90:93], v[164:167], v[204:207], v[90:93]
	v_mfma_f32_16x16x32_bf16 v[86:89], v[156:159], v[212:215], v[86:89]
	v_mfma_f32_16x16x32_bf16 v[82:85], v[164:167], v[212:215], v[82:85]
	v_mfma_f32_16x16x32_bf16 v[126:129], v[160:163], v[192:195], v[126:129]
	v_mfma_f32_16x16x32_bf16 v[122:125], v[168:171], v[192:195], v[122:125]
	v_mfma_f32_16x16x32_bf16 v[118:121], v[160:163], v[200:203], v[118:121]
	v_mfma_f32_16x16x32_bf16 v[114:117], v[168:171], v[200:203], v[114:117]
	v_mfma_f32_16x16x32_bf16 v[94:97], v[160:163], v[208:211], v[94:97]
	v_mfma_f32_16x16x32_bf16 v[90:93], v[168:171], v[208:211], v[90:93]
	v_mfma_f32_16x16x32_bf16 v[86:89], v[160:163], v[216:219], v[86:89]
	v_mfma_f32_16x16x32_bf16 v[82:85], v[168:171], v[216:219], v[82:85]
	v_mfma_f32_16x16x32_bf16 v[110:113], v[172:175], v[188:191], v[110:113]
	v_mfma_f32_16x16x32_bf16 v[106:109], v[180:183], v[188:191], v[106:109]
	v_mfma_f32_16x16x32_bf16 v[102:105], v[172:175], v[196:199], v[102:105]
	v_mfma_f32_16x16x32_bf16 v[98:101], v[180:183], v[196:199], v[98:101]
	v_mfma_f32_16x16x32_bf16 v[78:81], v[172:175], v[204:207], v[78:81]
	v_mfma_f32_16x16x32_bf16 v[74:77], v[180:183], v[204:207], v[74:77]
	v_mfma_f32_16x16x32_bf16 v[70:73], v[172:175], v[212:215], v[70:73]
	v_mfma_f32_16x16x32_bf16 v[66:69], v[180:183], v[212:215], v[66:69]
	v_mfma_f32_16x16x32_bf16 v[110:113], v[176:179], v[192:195], v[110:113]
	v_mfma_f32_16x16x32_bf16 v[106:109], v[184:187], v[192:195], v[106:109]
	v_mfma_f32_16x16x32_bf16 v[102:105], v[176:179], v[200:203], v[102:105]
	v_mfma_f32_16x16x32_bf16 v[98:101], v[184:187], v[200:203], v[98:101]
	v_mfma_f32_16x16x32_bf16 v[78:81], v[176:179], v[208:211], v[78:81]
	v_mfma_f32_16x16x32_bf16 v[74:77], v[184:187], v[208:211], v[74:77]
	v_mfma_f32_16x16x32_bf16 v[70:73], v[176:179], v[216:219], v[70:73]
	v_mfma_f32_16x16x32_bf16 v[66:69], v[184:187], v[216:219], v[66:69]
	s_barrier
	s_setprio 0
	s_sleep 1
	s_add_i32 s38, s55, s13
	v_lshl_add_u64 v[148:149], v[148:149], 0, s[6:7]
	s_mov_b32 m0, s38
	ds_read_b128 v[188:191], v155 offset:49152
	ds_read_b128 v[192:195], v155 offset:50176
	ds_read_b128 v[196:199], v155 offset:51200
	ds_read_b128 v[200:203], v155 offset:52224
	ds_read_b128 v[204:207], v155 offset:53248
	ds_read_b128 v[208:211], v155 offset:54272
	ds_read_b128 v[212:215], v155 offset:55296
	ds_read_b128 v[216:219], v155 offset:56320
	global_load_lds_dwordx4 v[148:149], off
	s_add_i32 m0, s38, 0x2000
	s_add_u32 s36, s36, 0x100080
	v_lshl_add_u64 v[148:149], v[220:221], 0, s[6:7]
	s_addc_u32 s37, s37, 0
	s_add_i32 s38, s56, s13
	global_load_lds_dwordx4 v[148:149], off
	v_lshl_add_u64 v[148:149], s[36:37], 0, v[134:135]
	s_mov_b32 m0, s38
	s_nop 0
	global_load_lds_dwordx4 v[148:149], off
	v_lshl_add_u64 v[148:149], s[36:37], 0, v[130:131]
	s_add_i32 m0, s38, 0x2000
	s_nop 0
	global_load_lds_dwordx4 v[148:149], off
	v_lshl_add_u64 v[148:149], v[224:225], 0, s[6:7]
	s_mov_b32 m0, s41
	s_nop 0
	global_load_lds_dwordx4 v[148:149], off
	v_lshl_add_u64 v[148:149], v[226:227], 0, s[6:7]
	s_mov_b32 m0, s42
	s_nop 0
	global_load_lds_dwordx4 v[148:149], off
	s_waitcnt vmcnt(8)
	s_waitcnt lgkmcnt(0)
	s_setprio 1
	s_barrier
	v_mfma_f32_16x16x32_bf16 v[62:65], v[156:159], v[188:191], v[62:65]
	v_mfma_f32_16x16x32_bf16 v[58:61], v[164:167], v[188:191], v[58:61]
	v_mfma_f32_16x16x32_bf16 v[54:57], v[156:159], v[196:199], v[54:57]
	v_mfma_f32_16x16x32_bf16 v[50:53], v[164:167], v[196:199], v[50:53]
	v_mfma_f32_16x16x32_bf16 v[30:33], v[156:159], v[204:207], v[30:33]
	v_mfma_f32_16x16x32_bf16 v[26:29], v[164:167], v[204:207], v[26:29]
	v_mfma_f32_16x16x32_bf16 v[22:25], v[156:159], v[212:215], v[22:25]
	v_mfma_f32_16x16x32_bf16 v[18:21], v[164:167], v[212:215], v[18:21]
	v_mfma_f32_16x16x32_bf16 v[62:65], v[160:163], v[192:195], v[62:65]
	v_mfma_f32_16x16x32_bf16 v[58:61], v[168:171], v[192:195], v[58:61]
	v_mfma_f32_16x16x32_bf16 v[54:57], v[160:163], v[200:203], v[54:57]
	v_mfma_f32_16x16x32_bf16 v[50:53], v[168:171], v[200:203], v[50:53]
	v_mfma_f32_16x16x32_bf16 v[30:33], v[160:163], v[208:211], v[30:33]
	v_mfma_f32_16x16x32_bf16 v[26:29], v[168:171], v[208:211], v[26:29]
	v_mfma_f32_16x16x32_bf16 v[22:25], v[160:163], v[216:219], v[22:25]
	v_mfma_f32_16x16x32_bf16 v[18:21], v[168:171], v[216:219], v[18:21]
	v_mfma_f32_16x16x32_bf16 v[46:49], v[172:175], v[188:191], v[46:49]
	v_mfma_f32_16x16x32_bf16 v[42:45], v[180:183], v[188:191], v[42:45]
	v_mfma_f32_16x16x32_bf16 v[38:41], v[172:175], v[196:199], v[38:41]
	v_mfma_f32_16x16x32_bf16 v[34:37], v[180:183], v[196:199], v[34:37]
	v_mfma_f32_16x16x32_bf16 v[14:17], v[172:175], v[204:207], v[14:17]
	v_mfma_f32_16x16x32_bf16 v[10:13], v[180:183], v[204:207], v[10:13]
	v_mfma_f32_16x16x32_bf16 v[6:9], v[172:175], v[212:215], v[6:9]
	v_mfma_f32_16x16x32_bf16 v[2:5], v[180:183], v[212:215], v[2:5]
	v_mfma_f32_16x16x32_bf16 v[46:49], v[176:179], v[192:195], v[46:49]
	v_mfma_f32_16x16x32_bf16 v[42:45], v[184:187], v[192:195], v[42:45]
	v_mfma_f32_16x16x32_bf16 v[38:41], v[176:179], v[200:203], v[38:41]
	v_mfma_f32_16x16x32_bf16 v[34:37], v[184:187], v[200:203], v[34:37]
	v_mfma_f32_16x16x32_bf16 v[14:17], v[176:179], v[208:211], v[14:17]
	v_mfma_f32_16x16x32_bf16 v[10:13], v[184:187], v[208:211], v[10:13]
	v_mfma_f32_16x16x32_bf16 v[6:9], v[176:179], v[216:219], v[6:9]
	v_mfma_f32_16x16x32_bf16 v[2:5], v[184:187], v[216:219], v[2:5]
	s_barrier
	s_setprio 0
	s_sleep 1
	s_add_i32 s54, s54, 2
	s_add_u32 s26, s26, 0x100
	s_addc_u32 s27, s27, 0
	s_add_u32 s52, s52, 0x100
	s_addc_u32 s53, s53, 0
	s_cmp_gt_u32 s54, 61
	s_cbranch_scc0 .LBB0_788
	s_and_b64 vcc, exec, s[8:9]
	s_cbranch_vccz .LBB0_791
	s_barrier

.Lpeeld:
	ds_read_b128 v[130:133], v207
	ds_read_b128 v[134:137], v207 offset:1024
	ds_read_b128 v[138:141], v207 offset:2048
	ds_read_b128 v[142:145], v207 offset:3072
	ds_read_b128 v[146:149], v208
	ds_read_b128 v[172:175], v208 offset:1024
	ds_read_b128 v[176:179], v208 offset:2048
	ds_read_b128 v[210:213], v208 offset:3072
	s_add_u32 s10, s8, 0xffd50080
	s_addc_u32 s11, s9, -1
	s_cmpk_eq_i32 s16, 0xa8
	s_cselect_b32 s13, s25, s11
	s_cselect_b32 s12, s24, s10
	s_cselect_b32 s11, s41, s15
	s_cselect_b32 s10, s40, s14
	v_lshl_add_u64 v[180:181], s[8:9], 0, v[166:167]
	s_add_i32 m0, s48, 0xc000
	ds_read_b128 v[214:217], v202
	ds_read_b128 v[218:221], v202 offset:1024
	ds_read_b128 v[224:227], v202 offset:2048
	ds_read_b128 v[228:231], v202 offset:3072
	ds_read_b128 v[232:235], v202 offset:4096
	ds_read_b128 v[236:239], v202 offset:5120
	ds_read_b128 v[240:243], v202 offset:6144
	ds_read_b128 v[244:247], v202 offset:7168
	global_load_lds_dwordx4 v[180:181], off
	v_lshl_add_u64 v[180:181], s[8:9], 0, v[168:169]
	s_add_i32 m0, s48, 0xe000
	s_nop 0
	global_load_lds_dwordx4 v[180:181], off
	s_waitcnt vmcnt(8)
	s_waitcnt lgkmcnt(0)
	s_setprio 1
	s_barrier
	v_mfma_f32_16x16x32_bf16 v[90:93], v[130:133], v[214:217], 0
	v_mfma_f32_16x16x32_bf16 v[74:77], v[138:141], v[214:217], 0
	v_mfma_f32_16x16x32_bf16 v[46:49], v[130:133], v[224:227], 0
	v_mfma_f32_16x16x32_bf16 v[42:45], v[138:141], v[224:227], 0
	v_mfma_f32_16x16x32_bf16 v[126:129], v[130:133], v[232:235], 0
	v_mfma_f32_16x16x32_bf16 v[122:125], v[138:141], v[232:235], 0
	v_mfma_f32_16x16x32_bf16 v[110:113], v[130:133], v[240:243], 0
	v_mfma_f32_16x16x32_bf16 v[106:109], v[138:141], v[240:243], 0
	v_mfma_f32_16x16x32_bf16 v[90:93], v[134:137], v[218:221], v[90:93]
	v_mfma_f32_16x16x32_bf16 v[74:77], v[142:145], v[218:221], v[74:77]
	v_mfma_f32_16x16x32_bf16 v[46:49], v[134:137], v[228:231], v[46:49]
	v_mfma_f32_16x16x32_bf16 v[42:45], v[142:145], v[228:231], v[42:45]
	v_mfma_f32_16x16x32_bf16 v[126:129], v[134:137], v[236:239], v[126:129]
	v_mfma_f32_16x16x32_bf16 v[122:125], v[142:145], v[236:239], v[122:125]
	v_mfma_f32_16x16x32_bf16 v[110:113], v[134:137], v[244:247], v[110:113]
	v_mfma_f32_16x16x32_bf16 v[106:109], v[142:145], v[244:247], v[106:109]
	v_mfma_f32_16x16x32_bf16 v[70:73], v[146:149], v[214:217], 0
	v_mfma_f32_16x16x32_bf16 v[66:69], v[176:179], v[214:217], 0
	v_mfma_f32_16x16x32_bf16 v[34:37], v[146:149], v[224:227], 0
	v_mfma_f32_16x16x32_bf16 v[38:41], v[176:179], v[224:227], 0
	v_mfma_f32_16x16x32_bf16 v[118:121], v[146:149], v[232:235], 0
	v_mfma_f32_16x16x32_bf16 v[114:117], v[176:179], v[232:235], 0
	v_mfma_f32_16x16x32_bf16 v[102:105], v[146:149], v[240:243], 0
	v_mfma_f32_16x16x32_bf16 v[98:101], v[176:179], v[240:243], 0
	v_mfma_f32_16x16x32_bf16 v[70:73], v[172:175], v[218:221], v[70:73]
	v_mfma_f32_16x16x32_bf16 v[66:69], v[210:213], v[218:221], v[66:69]
	v_mfma_f32_16x16x32_bf16 v[34:37], v[172:175], v[228:231], v[34:37]
	v_mfma_f32_16x16x32_bf16 v[38:41], v[210:213], v[228:231], v[38:41]
	v_mfma_f32_16x16x32_bf16 v[118:121], v[172:175], v[236:239], v[118:121]
	v_mfma_f32_16x16x32_bf16 v[114:117], v[210:213], v[236:239], v[114:117]
	v_mfma_f32_16x16x32_bf16 v[102:105], v[172:175], v[244:247], v[102:105]
	v_mfma_f32_16x16x32_bf16 v[98:101], v[210:213], v[244:247], v[98:101]
	s_barrier
	s_setprio 0
	s_sleep 1
	s_add_i32 s17, s57, s46
	v_lshl_add_u64 v[180:181], s[10:11], 0, v[150:151]
	s_mov_b32 m0, s17
	ds_read_b128 v[214:217], v202 offset:16384
	ds_read_b128 v[218:221], v202 offset:17408
	ds_read_b128 v[224:227], v202 offset:18432
	ds_read_b128 v[228:231], v202 offset:19456
	ds_read_b128 v[232:235], v202 offset:20480
	ds_read_b128 v[236:239], v202 offset:21504
	ds_read_b128 v[240:243], v202 offset:22528
	ds_read_b128 v[244:247], v202 offset:23552
	global_load_lds_dwordx4 v[180:181], off
	s_add_i32 m0, s17, 0x2000
	s_add_u32 s18, s10, 0x2b0000
	v_lshl_add_u64 v[248:249], s[10:11], 0, v[152:153]
	s_addc_u32 s19, s11, 0
	s_add_i32 s17, s58, s46
	global_load_lds_dwordx4 v[248:249], off
	v_lshl_add_u64 v[250:251], s[18:19], 0, v[150:151]
	s_mov_b32 m0, s17
	v_lshl_add_u64 v[252:253], s[12:13], 0, v[152:153]
	global_load_lds_dwordx4 v[250:251], off
	v_lshl_add_u64 v[250:251], s[18:19], 0, v[152:153]
	s_add_i32 m0, s17, 0x2000
	s_nop 0
	global_load_lds_dwordx4 v[250:251], off
	v_lshl_add_u64 v[250:251], s[12:13], 0, v[150:151]
	s_mov_b32 m0, s48
	s_nop 0
	global_load_lds_dwordx4 v[250:251], off
	s_mov_b32 m0, s49
	s_nop 0
	global_load_lds_dwordx4 v[252:253], off
	s_waitcnt vmcnt(8)
	s_waitcnt lgkmcnt(0)
	s_setprio 1
	s_barrier
	v_mfma_f32_16x16x32_bf16 v[94:97], v[130:133], v[214:217], 0
	v_mfma_f32_16x16x32_bf16 v[86:89], v[138:141], v[214:217], 0
	v_mfma_f32_16x16x32_bf16 v[82:85], v[130:133], v[224:227], 0
	v_mfma_f32_16x16x32_bf16 v[78:81], v[138:141], v[224:227], 0
	v_mfma_f32_16x16x32_bf16 v[30:33], v[130:133], v[232:235], 0
	v_mfma_f32_16x16x32_bf16 v[26:29], v[138:141], v[232:235], 0
	v_mfma_f32_16x16x32_bf16 v[22:25], v[130:133], v[240:243], 0
	v_mfma_f32_16x16x32_bf16 v[18:21], v[138:141], v[240:243], 0
	v_mfma_f32_16x16x32_bf16 v[94:97], v[134:137], v[218:221], v[94:97]
	v_mfma_f32_16x16x32_bf16 v[86:89], v[142:145], v[218:221], v[86:89]
	v_mfma_f32_16x16x32_bf16 v[82:85], v[134:137], v[228:231], v[82:85]
	v_mfma_f32_16x16x32_bf16 v[78:81], v[142:145], v[228:231], v[78:81]
	v_mfma_f32_16x16x32_bf16 v[30:33], v[134:137], v[236:239], v[30:33]
	v_mfma_f32_16x16x32_bf16 v[26:29], v[142:145], v[236:239], v[26:29]
	v_mfma_f32_16x16x32_bf16 v[22:25], v[134:137], v[244:247], v[22:25]
	v_mfma_f32_16x16x32_bf16 v[18:21], v[142:145], v[244:247], v[18:21]
	v_mfma_f32_16x16x32_bf16 v[62:65], v[146:149], v[214:217], 0
	v_mfma_f32_16x16x32_bf16 v[58:61], v[176:179], v[214:217], 0
	v_mfma_f32_16x16x32_bf16 v[54:57], v[146:149], v[224:227], 0
	v_mfma_f32_16x16x32_bf16 v[50:53], v[176:179], v[224:227], 0
	v_mfma_f32_16x16x32_bf16 v[14:17], v[146:149], v[232:235], 0
	v_mfma_f32_16x16x32_bf16 v[6:9], v[176:179], v[232:235], 0
	v_mfma_f32_16x16x32_bf16 v[10:13], v[146:149], v[240:243], 0
	v_mfma_f32_16x16x32_bf16 v[2:5], v[176:179], v[240:243], 0
	v_mfma_f32_16x16x32_bf16 v[62:65], v[172:175], v[218:221], v[62:65]
	v_mfma_f32_16x16x32_bf16 v[58:61], v[210:213], v[218:221], v[58:61]
	v_mfma_f32_16x16x32_bf16 v[54:57], v[172:175], v[228:231], v[54:57]
	v_mfma_f32_16x16x32_bf16 v[50:53], v[210:213], v[228:231], v[50:53]
	v_mfma_f32_16x16x32_bf16 v[14:17], v[172:175], v[236:239], v[14:17]
	v_mfma_f32_16x16x32_bf16 v[6:9], v[210:213], v[236:239], v[6:9]
	v_mfma_f32_16x16x32_bf16 v[10:13], v[172:175], v[244:247], v[10:13]
	v_mfma_f32_16x16x32_bf16 v[2:5], v[210:213], v[244:247], v[2:5]
	s_barrier
	s_setprio 0
	s_sleep 1
	s_add_i32 s17, 0, 0x18000
	s_add_i32 s18, 0, 0x1c000
	v_add_u32_e32 v142, s17, v182
	v_add_u32_e32 v154, s18, v182
	ds_read_b128 v[130:133], v142
	ds_read_b128 v[134:137], v142 offset:1024
	ds_read_b128 v[138:141], v142 offset:2048
	ds_read_b128 v[142:145], v142 offset:3072
	ds_read_b128 v[146:149], v154
	ds_read_b128 v[172:175], v154 offset:1024
	ds_read_b128 v[176:179], v154 offset:2048
	ds_read_b128 v[210:213], v154 offset:3072
	s_add_u32 s12, s12, 0x2b0000
	s_addc_u32 s13, s13, 0
	s_mov_b32 m0, s50
	v_lshl_add_u64 v[188:189], s[12:13], 0, v[150:151]
	ds_read_b128 v[214:217], v202 offset:32768
	ds_read_b128 v[218:221], v202 offset:33792
	ds_read_b128 v[224:227], v202 offset:34816
	ds_read_b128 v[228:231], v202 offset:35840
	ds_read_b128 v[232:235], v202 offset:36864
	ds_read_b128 v[236:239], v202 offset:37888
	ds_read_b128 v[240:243], v202 offset:38912
	ds_read_b128 v[244:247], v202 offset:39936
	global_load_lds_dwordx4 v[188:189], off
	v_lshl_add_u64 v[188:189], s[12:13], 0, v[152:153]
	s_mov_b32 m0, s51
	s_nop 0
	global_load_lds_dwordx4 v[188:189], off
	s_waitcnt vmcnt(8)
	s_waitcnt lgkmcnt(0)
	s_setprio 1
	s_barrier
	v_mfma_f32_16x16x32_bf16 v[90:93], v[130:133], v[214:217], v[90:93]
	v_mfma_f32_16x16x32_bf16 v[74:77], v[138:141], v[214:217], v[74:77]
	v_mfma_f32_16x16x32_bf16 v[46:49], v[130:133], v[224:227], v[46:49]
	v_mfma_f32_16x16x32_bf16 v[42:45], v[138:141], v[224:227], v[42:45]
	v_mfma_f32_16x16x32_bf16 v[126:129], v[130:133], v[232:235], v[126:129]
	v_mfma_f32_16x16x32_bf16 v[122:125], v[138:141], v[232:235], v[122:125]
	v_mfma_f32_16x16x32_bf16 v[110:113], v[130:133], v[240:243], v[110:113]
	v_mfma_f32_16x16x32_bf16 v[106:109], v[138:141], v[240:243], v[106:109]
	v_mfma_f32_16x16x32_bf16 v[90:93], v[134:137], v[218:221], v[90:93]
	v_mfma_f32_16x16x32_bf16 v[74:77], v[142:145], v[218:221], v[74:77]
	v_mfma_f32_16x16x32_bf16 v[46:49], v[134:137], v[228:231], v[46:49]
	v_mfma_f32_16x16x32_bf16 v[42:45], v[142:145], v[228:231], v[42:45]
	v_mfma_f32_16x16x32_bf16 v[126:129], v[134:137], v[236:239], v[126:129]
	v_mfma_f32_16x16x32_bf16 v[122:125], v[142:145], v[236:239], v[122:125]
	v_mfma_f32_16x16x32_bf16 v[110:113], v[134:137], v[244:247], v[110:113]
	v_mfma_f32_16x16x32_bf16 v[106:109], v[142:145], v[244:247], v[106:109]
	v_mfma_f32_16x16x32_bf16 v[70:73], v[146:149], v[214:217], v[70:73]
	v_mfma_f32_16x16x32_bf16 v[66:69], v[176:179], v[214:217], v[66:69]
	v_mfma_f32_16x16x32_bf16 v[34:37], v[146:149], v[224:227], v[34:37]
	v_mfma_f32_16x16x32_bf16 v[38:41], v[176:179], v[224:227], v[38:41]
	v_mfma_f32_16x16x32_bf16 v[118:121], v[146:149], v[232:235], v[118:121]
	v_mfma_f32_16x16x32_bf16 v[114:117], v[176:179], v[232:235], v[114:117]
	v_mfma_f32_16x16x32_bf16 v[102:105], v[146:149], v[240:243], v[102:105]
	v_mfma_f32_16x16x32_bf16 v[98:101], v[176:179], v[240:243], v[98:101]
	v_mfma_f32_16x16x32_bf16 v[70:73], v[172:175], v[218:221], v[70:73]
	v_mfma_f32_16x16x32_bf16 v[66:69], v[210:213], v[218:221], v[66:69]
	v_mfma_f32_16x16x32_bf16 v[34:37], v[172:175], v[228:231], v[34:37]
	v_mfma_f32_16x16x32_bf16 v[38:41], v[210:213], v[228:231], v[38:41]
	v_mfma_f32_16x16x32_bf16 v[118:121], v[172:175], v[236:239], v[118:121]
	v_mfma_f32_16x16x32_bf16 v[114:117], v[210:213], v[236:239], v[114:117]
	v_mfma_f32_16x16x32_bf16 v[102:105], v[172:175], v[244:247], v[102:105]
	v_mfma_f32_16x16x32_bf16 v[98:101], v[210:213], v[244:247], v[98:101]
	s_barrier
	s_setprio 0
	s_sleep 1
	s_add_i32 s12, s17, s46
	v_lshl_add_u64 v[180:181], v[180:181], 0, s[30:31]
	s_mov_b32 m0, s12
	ds_read_b128 v[214:217], v202 offset:49152
	ds_read_b128 v[218:221], v202 offset:50176
	ds_read_b128 v[224:227], v202 offset:51200
	ds_read_b128 v[228:231], v202 offset:52224
	ds_read_b128 v[232:235], v202 offset:53248
	ds_read_b128 v[236:239], v202 offset:54272
	ds_read_b128 v[240:243], v202 offset:55296
	ds_read_b128 v[244:247], v202 offset:56320
	global_load_lds_dwordx4 v[180:181], off
	s_add_i32 m0, s12, 0x2000
	s_add_u32 s10, s10, 0x2b0080
	v_lshl_add_u64 v[180:181], v[248:249], 0, s[30:31]
	s_addc_u32 s11, s11, 0
	s_add_i32 s12, s18, s46
	global_load_lds_dwordx4 v[180:181], off
	v_lshl_add_u64 v[180:181], s[10:11], 0, v[150:151]
	s_mov_b32 m0, s12
	s_nop 0
	global_load_lds_dwordx4 v[180:181], off
	v_lshl_add_u64 v[180:181], s[10:11], 0, v[152:153]
	s_add_i32 m0, s12, 0x2000
	s_nop 0
	global_load_lds_dwordx4 v[180:181], off
	v_lshl_add_u64 v[180:181], v[250:251], 0, s[30:31]
	s_mov_b32 m0, s52
	s_nop 0
	global_load_lds_dwordx4 v[180:181], off
	v_lshl_add_u64 v[180:181], v[252:253], 0, s[30:31]
	s_mov_b32 m0, s53
	s_nop 0
	global_load_lds_dwordx4 v[180:181], off
	s_waitcnt vmcnt(8)
	s_waitcnt lgkmcnt(0)
	s_setprio 1
	s_barrier
	v_mfma_f32_16x16x32_bf16 v[94:97], v[130:133], v[214:217], v[94:97]
	v_mfma_f32_16x16x32_bf16 v[86:89], v[138:141], v[214:217], v[86:89]
	v_mfma_f32_16x16x32_bf16 v[82:85], v[130:133], v[224:227], v[82:85]
	v_mfma_f32_16x16x32_bf16 v[78:81], v[138:141], v[224:227], v[78:81]
	v_mfma_f32_16x16x32_bf16 v[30:33], v[130:133], v[232:235], v[30:33]
	v_mfma_f32_16x16x32_bf16 v[26:29], v[138:141], v[232:235], v[26:29]
	v_mfma_f32_16x16x32_bf16 v[22:25], v[130:133], v[240:243], v[22:25]
	v_mfma_f32_16x16x32_bf16 v[18:21], v[138:141], v[240:243], v[18:21]
	v_mfma_f32_16x16x32_bf16 v[94:97], v[134:137], v[218:221], v[94:97]
	v_mfma_f32_16x16x32_bf16 v[86:89], v[142:145], v[218:221], v[86:89]
	v_mfma_f32_16x16x32_bf16 v[82:85], v[134:137], v[228:231], v[82:85]
	v_mfma_f32_16x16x32_bf16 v[78:81], v[142:145], v[228:231], v[78:81]
	v_mfma_f32_16x16x32_bf16 v[30:33], v[134:137], v[236:239], v[30:33]
	v_mfma_f32_16x16x32_bf16 v[26:29], v[142:145], v[236:239], v[26:29]
	v_mfma_f32_16x16x32_bf16 v[22:25], v[134:137], v[244:247], v[22:25]
	v_mfma_f32_16x16x32_bf16 v[18:21], v[142:145], v[244:247], v[18:21]
	v_mfma_f32_16x16x32_bf16 v[62:65], v[146:149], v[214:217], v[62:65]
	v_mfma_f32_16x16x32_bf16 v[58:61], v[176:179], v[214:217], v[58:61]
	v_mfma_f32_16x16x32_bf16 v[54:57], v[146:149], v[224:227], v[54:57]
	v_mfma_f32_16x16x32_bf16 v[50:53], v[176:179], v[224:227], v[50:53]
	v_mfma_f32_16x16x32_bf16 v[14:17], v[146:149], v[232:235], v[14:17]
	v_mfma_f32_16x16x32_bf16 v[6:9], v[176:179], v[232:235], v[6:9]
	v_mfma_f32_16x16x32_bf16 v[10:13], v[146:149], v[240:243], v[10:13]
	v_mfma_f32_16x16x32_bf16 v[2:5], v[176:179], v[240:243], v[2:5]
	v_mfma_f32_16x16x32_bf16 v[62:65], v[172:175], v[218:221], v[62:65]
	v_mfma_f32_16x16x32_bf16 v[58:61], v[210:213], v[218:221], v[58:61]
	v_mfma_f32_16x16x32_bf16 v[54:57], v[172:175], v[228:231], v[54:57]
	v_mfma_f32_16x16x32_bf16 v[50:53], v[210:213], v[228:231], v[50:53]
	v_mfma_f32_16x16x32_bf16 v[14:17], v[172:175], v[236:239], v[14:17]
	v_mfma_f32_16x16x32_bf16 v[6:9], v[210:213], v[236:239], v[6:9]
	v_mfma_f32_16x16x32_bf16 v[10:13], v[172:175], v[244:247], v[10:13]
	v_mfma_f32_16x16x32_bf16 v[2:5], v[210:213], v[244:247], v[2:5]
	s_barrier
	s_setprio 0
	s_sleep 1
	s_add_i32 s16, s16, 2
	s_add_u32 s8, s8, 0x100
	s_addc_u32 s9, s9, 0
	s_add_u32 s14, s14, 0x100
	s_addc_u32 s15, s15, 0
.LBB0_1040:
	ds_read_b128 v[130:133], v207
	ds_read_b128 v[134:137], v207 offset:1024
	ds_read_b128 v[138:141], v207 offset:2048
	ds_read_b128 v[142:145], v207 offset:3072
	ds_read_b128 v[146:149], v208
	ds_read_b128 v[172:175], v208 offset:1024
	ds_read_b128 v[176:179], v208 offset:2048
	ds_read_b128 v[210:213], v208 offset:3072
	s_add_u32 s10, s8, 0xffd50080
	s_addc_u32 s11, s9, -1
	s_cmpk_eq_i32 s16, 0xa8
	s_cselect_b32 s13, s25, s11
	s_cselect_b32 s12, s24, s10
	s_cselect_b32 s11, s41, s15
	s_cselect_b32 s10, s40, s14
	v_lshl_add_u64 v[180:181], s[8:9], 0, v[166:167]
	s_add_i32 m0, s48, 0xc000
	ds_read_b128 v[214:217], v202
	ds_read_b128 v[218:221], v202 offset:1024
	ds_read_b128 v[224:227], v202 offset:2048
	ds_read_b128 v[228:231], v202 offset:3072
	ds_read_b128 v[232:235], v202 offset:4096
	ds_read_b128 v[236:239], v202 offset:5120
	ds_read_b128 v[240:243], v202 offset:6144
	ds_read_b128 v[244:247], v202 offset:7168
	global_load_lds_dwordx4 v[180:181], off
	v_lshl_add_u64 v[180:181], s[8:9], 0, v[168:169]
	s_add_i32 m0, s48, 0xe000
	s_nop 0
	global_load_lds_dwordx4 v[180:181], off
	s_waitcnt vmcnt(8)
	s_waitcnt lgkmcnt(0)
	s_setprio 1
	s_barrier
	v_mfma_f32_16x16x32_bf16 v[90:93], v[130:133], v[214:217], v[90:93]
	v_mfma_f32_16x16x32_bf16 v[74:77], v[138:141], v[214:217], v[74:77]
	v_mfma_f32_16x16x32_bf16 v[46:49], v[130:133], v[224:227], v[46:49]
	v_mfma_f32_16x16x32_bf16 v[42:45], v[138:141], v[224:227], v[42:45]
	v_mfma_f32_16x16x32_bf16 v[126:129], v[130:133], v[232:235], v[126:129]
	v_mfma_f32_16x16x32_bf16 v[122:125], v[138:141], v[232:235], v[122:125]
	v_mfma_f32_16x16x32_bf16 v[110:113], v[130:133], v[240:243], v[110:113]
	v_mfma_f32_16x16x32_bf16 v[106:109], v[138:141], v[240:243], v[106:109]
	v_mfma_f32_16x16x32_bf16 v[90:93], v[134:137], v[218:221], v[90:93]
	v_mfma_f32_16x16x32_bf16 v[74:77], v[142:145], v[218:221], v[74:77]
	v_mfma_f32_16x16x32_bf16 v[46:49], v[134:137], v[228:231], v[46:49]
	v_mfma_f32_16x16x32_bf16 v[42:45], v[142:145], v[228:231], v[42:45]
	v_mfma_f32_16x16x32_bf16 v[126:129], v[134:137], v[236:239], v[126:129]
	v_mfma_f32_16x16x32_bf16 v[122:125], v[142:145], v[236:239], v[122:125]
	v_mfma_f32_16x16x32_bf16 v[110:113], v[134:137], v[244:247], v[110:113]
	v_mfma_f32_16x16x32_bf16 v[106:109], v[142:145], v[244:247], v[106:109]
	v_mfma_f32_16x16x32_bf16 v[70:73], v[146:149], v[214:217], v[70:73]
	v_mfma_f32_16x16x32_bf16 v[66:69], v[176:179], v[214:217], v[66:69]
	v_mfma_f32_16x16x32_bf16 v[34:37], v[146:149], v[224:227], v[34:37]
	v_mfma_f32_16x16x32_bf16 v[38:41], v[176:179], v[224:227], v[38:41]
	v_mfma_f32_16x16x32_bf16 v[118:121], v[146:149], v[232:235], v[118:121]
	v_mfma_f32_16x16x32_bf16 v[114:117], v[176:179], v[232:235], v[114:117]
	v_mfma_f32_16x16x32_bf16 v[102:105], v[146:149], v[240:243], v[102:105]
	v_mfma_f32_16x16x32_bf16 v[98:101], v[176:179], v[240:243], v[98:101]
	v_mfma_f32_16x16x32_bf16 v[70:73], v[172:175], v[218:221], v[70:73]
	v_mfma_f32_16x16x32_bf16 v[66:69], v[210:213], v[218:221], v[66:69]
	v_mfma_f32_16x16x32_bf16 v[34:37], v[172:175], v[228:231], v[34:37]
	v_mfma_f32_16x16x32_bf16 v[38:41], v[210:213], v[228:231], v[38:41]
	v_mfma_f32_16x16x32_bf16 v[118:121], v[172:175], v[236:239], v[118:121]
	v_mfma_f32_16x16x32_bf16 v[114:117], v[210:213], v[236:239], v[114:117]
	v_mfma_f32_16x16x32_bf16 v[102:105], v[172:175], v[244:247], v[102:105]
	v_mfma_f32_16x16x32_bf16 v[98:101], v[210:213], v[244:247], v[98:101]
	s_barrier
	s_setprio 0
	s_sleep 1
	s_add_i32 s17, s57, s46
	v_lshl_add_u64 v[180:181], s[10:11], 0, v[150:151]
	s_mov_b32 m0, s17
	ds_read_b128 v[214:217], v202 offset:16384
	ds_read_b128 v[218:221], v202 offset:17408
	ds_read_b128 v[224:227], v202 offset:18432
	ds_read_b128 v[228:231], v202 offset:19456
	ds_read_b128 v[232:235], v202 offset:20480
	ds_read_b128 v[236:239], v202 offset:21504
	ds_read_b128 v[240:243], v202 offset:22528
	ds_read_b128 v[244:247], v202 offset:23552
	global_load_lds_dwordx4 v[180:181], off
	s_add_i32 m0, s17, 0x2000
	s_add_u32 s18, s10, 0x2b0000
	v_lshl_add_u64 v[248:249], s[10:11], 0, v[152:153]
	s_addc_u32 s19, s11, 0
	s_add_i32 s17, s58, s46
	global_load_lds_dwordx4 v[248:249], off
	v_lshl_add_u64 v[250:251], s[18:19], 0, v[150:151]
	s_mov_b32 m0, s17
	v_lshl_add_u64 v[252:253], s[12:13], 0, v[152:153]
	global_load_lds_dwordx4 v[250:251], off
	v_lshl_add_u64 v[250:251], s[18:19], 0, v[152:153]
	s_add_i32 m0, s17, 0x2000
	s_nop 0
	global_load_lds_dwordx4 v[250:251], off
	v_lshl_add_u64 v[250:251], s[12:13], 0, v[150:151]
	s_mov_b32 m0, s48
	s_nop 0
	global_load_lds_dwordx4 v[250:251], off
	s_mov_b32 m0, s49
	s_nop 0
	global_load_lds_dwordx4 v[252:253], off
	s_waitcnt vmcnt(8)
	s_waitcnt lgkmcnt(0)
	s_setprio 1
	s_barrier
	v_mfma_f32_16x16x32_bf16 v[94:97], v[130:133], v[214:217], v[94:97]
	v_mfma_f32_16x16x32_bf16 v[86:89], v[138:141], v[214:217], v[86:89]
	v_mfma_f32_16x16x32_bf16 v[82:85], v[130:133], v[224:227], v[82:85]
	v_mfma_f32_16x16x32_bf16 v[78:81], v[138:141], v[224:227], v[78:81]
	v_mfma_f32_16x16x32_bf16 v[30:33], v[130:133], v[232:235], v[30:33]
	v_mfma_f32_16x16x32_bf16 v[26:29], v[138:141], v[232:235], v[26:29]
	v_mfma_f32_16x16x32_bf16 v[22:25], v[130:133], v[240:243], v[22:25]
	v_mfma_f32_16x16x32_bf16 v[18:21], v[138:141], v[240:243], v[18:21]
	v_mfma_f32_16x16x32_bf16 v[94:97], v[134:137], v[218:221], v[94:97]
	v_mfma_f32_16x16x32_bf16 v[86:89], v[142:145], v[218:221], v[86:89]
	v_mfma_f32_16x16x32_bf16 v[82:85], v[134:137], v[228:231], v[82:85]
	v_mfma_f32_16x16x32_bf16 v[78:81], v[142:145], v[228:231], v[78:81]
	v_mfma_f32_16x16x32_bf16 v[30:33], v[134:137], v[236:239], v[30:33]
	v_mfma_f32_16x16x32_bf16 v[26:29], v[142:145], v[236:239], v[26:29]
	v_mfma_f32_16x16x32_bf16 v[22:25], v[134:137], v[244:247], v[22:25]
	v_mfma_f32_16x16x32_bf16 v[18:21], v[142:145], v[244:247], v[18:21]
	v_mfma_f32_16x16x32_bf16 v[62:65], v[146:149], v[214:217], v[62:65]
	v_mfma_f32_16x16x32_bf16 v[58:61], v[176:179], v[214:217], v[58:61]
	v_mfma_f32_16x16x32_bf16 v[54:57], v[146:149], v[224:227], v[54:57]
	v_mfma_f32_16x16x32_bf16 v[50:53], v[176:179], v[224:227], v[50:53]
	v_mfma_f32_16x16x32_bf16 v[14:17], v[146:149], v[232:235], v[14:17]
	v_mfma_f32_16x16x32_bf16 v[6:9], v[176:179], v[232:235], v[6:9]
	v_mfma_f32_16x16x32_bf16 v[10:13], v[146:149], v[240:243], v[10:13]
	v_mfma_f32_16x16x32_bf16 v[2:5], v[176:179], v[240:243], v[2:5]
	v_mfma_f32_16x16x32_bf16 v[62:65], v[172:175], v[218:221], v[62:65]
	v_mfma_f32_16x16x32_bf16 v[58:61], v[210:213], v[218:221], v[58:61]
	v_mfma_f32_16x16x32_bf16 v[54:57], v[172:175], v[228:231], v[54:57]
	v_mfma_f32_16x16x32_bf16 v[50:53], v[210:213], v[228:231], v[50:53]
	v_mfma_f32_16x16x32_bf16 v[14:17], v[172:175], v[236:239], v[14:17]
	v_mfma_f32_16x16x32_bf16 v[6:9], v[210:213], v[236:239], v[6:9]
	v_mfma_f32_16x16x32_bf16 v[10:13], v[172:175], v[244:247], v[10:13]
	v_mfma_f32_16x16x32_bf16 v[2:5], v[210:213], v[244:247], v[2:5]
	s_barrier
	s_setprio 0
	s_sleep 1
	s_add_i32 s17, 0, 0x18000
	s_add_i32 s18, 0, 0x1c000
	v_add_u32_e32 v142, s17, v182
	v_add_u32_e32 v154, s18, v182
	ds_read_b128 v[130:133], v142
	ds_read_b128 v[134:137], v142 offset:1024
	ds_read_b128 v[138:141], v142 offset:2048
	ds_read_b128 v[142:145], v142 offset:3072
	ds_read_b128 v[146:149], v154
	ds_read_b128 v[172:175], v154 offset:1024
	ds_read_b128 v[176:179], v154 offset:2048
	ds_read_b128 v[210:213], v154 offset:3072
	s_add_u32 s12, s12, 0x2b0000
	s_addc_u32 s13, s13, 0
	s_mov_b32 m0, s50
	v_lshl_add_u64 v[188:189], s[12:13], 0, v[150:151]
	ds_read_b128 v[214:217], v202 offset:32768
	ds_read_b128 v[218:221], v202 offset:33792
	ds_read_b128 v[224:227], v202 offset:34816
	ds_read_b128 v[228:231], v202 offset:35840
	ds_read_b128 v[232:235], v202 offset:36864
	ds_read_b128 v[236:239], v202 offset:37888
	ds_read_b128 v[240:243], v202 offset:38912
	ds_read_b128 v[244:247], v202 offset:39936
	global_load_lds_dwordx4 v[188:189], off
	v_lshl_add_u64 v[188:189], s[12:13], 0, v[152:153]
	s_mov_b32 m0, s51
	s_nop 0
	global_load_lds_dwordx4 v[188:189], off
	s_waitcnt vmcnt(8)
	s_waitcnt lgkmcnt(0)
	s_setprio 1
	s_barrier
	v_mfma_f32_16x16x32_bf16 v[90:93], v[130:133], v[214:217], v[90:93]
	v_mfma_f32_16x16x32_bf16 v[74:77], v[138:141], v[214:217], v[74:77]
	v_mfma_f32_16x16x32_bf16 v[46:49], v[130:133], v[224:227], v[46:49]
	v_mfma_f32_16x16x32_bf16 v[42:45], v[138:141], v[224:227], v[42:45]
	v_mfma_f32_16x16x32_bf16 v[126:129], v[130:133], v[232:235], v[126:129]
	v_mfma_f32_16x16x32_bf16 v[122:125], v[138:141], v[232:235], v[122:125]
	v_mfma_f32_16x16x32_bf16 v[110:113], v[130:133], v[240:243], v[110:113]
	v_mfma_f32_16x16x32_bf16 v[106:109], v[138:141], v[240:243], v[106:109]
	v_mfma_f32_16x16x32_bf16 v[90:93], v[134:137], v[218:221], v[90:93]
	v_mfma_f32_16x16x32_bf16 v[74:77], v[142:145], v[218:221], v[74:77]
	v_mfma_f32_16x16x32_bf16 v[46:49], v[134:137], v[228:231], v[46:49]
	v_mfma_f32_16x16x32_bf16 v[42:45], v[142:145], v[228:231], v[42:45]
	v_mfma_f32_16x16x32_bf16 v[126:129], v[134:137], v[236:239], v[126:129]
	v_mfma_f32_16x16x32_bf16 v[122:125], v[142:145], v[236:239], v[122:125]
	v_mfma_f32_16x16x32_bf16 v[110:113], v[134:137], v[244:247], v[110:113]
	v_mfma_f32_16x16x32_bf16 v[106:109], v[142:145], v[244:247], v[106:109]
	v_mfma_f32_16x16x32_bf16 v[70:73], v[146:149], v[214:217], v[70:73]
	v_mfma_f32_16x16x32_bf16 v[66:69], v[176:179], v[214:217], v[66:69]
	v_mfma_f32_16x16x32_bf16 v[34:37], v[146:149], v[224:227], v[34:37]
	v_mfma_f32_16x16x32_bf16 v[38:41], v[176:179], v[224:227], v[38:41]
	v_mfma_f32_16x16x32_bf16 v[118:121], v[146:149], v[232:235], v[118:121]
	v_mfma_f32_16x16x32_bf16 v[114:117], v[176:179], v[232:235], v[114:117]
	v_mfma_f32_16x16x32_bf16 v[102:105], v[146:149], v[240:243], v[102:105]
	v_mfma_f32_16x16x32_bf16 v[98:101], v[176:179], v[240:243], v[98:101]
	v_mfma_f32_16x16x32_bf16 v[70:73], v[172:175], v[218:221], v[70:73]
	v_mfma_f32_16x16x32_bf16 v[66:69], v[210:213], v[218:221], v[66:69]
	v_mfma_f32_16x16x32_bf16 v[34:37], v[172:175], v[228:231], v[34:37]
	v_mfma_f32_16x16x32_bf16 v[38:41], v[210:213], v[228:231], v[38:41]
	v_mfma_f32_16x16x32_bf16 v[118:121], v[172:175], v[236:239], v[118:121]
	v_mfma_f32_16x16x32_bf16 v[114:117], v[210:213], v[236:239], v[114:117]
	v_mfma_f32_16x16x32_bf16 v[102:105], v[172:175], v[244:247], v[102:105]
	v_mfma_f32_16x16x32_bf16 v[98:101], v[210:213], v[244:247], v[98:101]
	s_barrier
	s_setprio 0
	s_sleep 1
	s_add_i32 s12, s17, s46
	v_lshl_add_u64 v[180:181], v[180:181], 0, s[30:31]
	s_mov_b32 m0, s12
	ds_read_b128 v[214:217], v202 offset:49152
	ds_read_b128 v[218:221], v202 offset:50176
	ds_read_b128 v[224:227], v202 offset:51200
	ds_read_b128 v[228:231], v202 offset:52224
	ds_read_b128 v[232:235], v202 offset:53248
	ds_read_b128 v[236:239], v202 offset:54272
	ds_read_b128 v[240:243], v202 offset:55296
	ds_read_b128 v[244:247], v202 offset:56320
	global_load_lds_dwordx4 v[180:181], off
	s_add_i32 m0, s12, 0x2000
	s_add_u32 s10, s10, 0x2b0080
	v_lshl_add_u64 v[180:181], v[248:249], 0, s[30:31]
	s_addc_u32 s11, s11, 0
	s_add_i32 s12, s18, s46
	global_load_lds_dwordx4 v[180:181], off
	v_lshl_add_u64 v[180:181], s[10:11], 0, v[150:151]
	s_mov_b32 m0, s12
	s_nop 0
	global_load_lds_dwordx4 v[180:181], off
	v_lshl_add_u64 v[180:181], s[10:11], 0, v[152:153]
	s_add_i32 m0, s12, 0x2000
	s_nop 0
	global_load_lds_dwordx4 v[180:181], off
	v_lshl_add_u64 v[180:181], v[250:251], 0, s[30:31]
	s_mov_b32 m0, s52
	s_nop 0
	global_load_lds_dwordx4 v[180:181], off
	v_lshl_add_u64 v[180:181], v[252:253], 0, s[30:31]
	s_mov_b32 m0, s53
	s_nop 0
	global_load_lds_dwordx4 v[180:181], off
	s_waitcnt vmcnt(8)
	s_waitcnt lgkmcnt(0)
	s_setprio 1
	s_barrier
	v_mfma_f32_16x16x32_bf16 v[94:97], v[130:133], v[214:217], v[94:97]
	v_mfma_f32_16x16x32_bf16 v[86:89], v[138:141], v[214:217], v[86:89]
	v_mfma_f32_16x16x32_bf16 v[82:85], v[130:133], v[224:227], v[82:85]
	v_mfma_f32_16x16x32_bf16 v[78:81], v[138:141], v[224:227], v[78:81]
	v_mfma_f32_16x16x32_bf16 v[30:33], v[130:133], v[232:235], v[30:33]
	v_mfma_f32_16x16x32_bf16 v[26:29], v[138:141], v[232:235], v[26:29]
	v_mfma_f32_16x16x32_bf16 v[22:25], v[130:133], v[240:243], v[22:25]
	v_mfma_f32_16x16x32_bf16 v[18:21], v[138:141], v[240:243], v[18:21]
	v_mfma_f32_16x16x32_bf16 v[94:97], v[134:137], v[218:221], v[94:97]
	v_mfma_f32_16x16x32_bf16 v[86:89], v[142:145], v[218:221], v[86:89]
	v_mfma_f32_16x16x32_bf16 v[82:85], v[134:137], v[228:231], v[82:85]
	v_mfma_f32_16x16x32_bf16 v[78:81], v[142:145], v[228:231], v[78:81]
	v_mfma_f32_16x16x32_bf16 v[30:33], v[134:137], v[236:239], v[30:33]
	v_mfma_f32_16x16x32_bf16 v[26:29], v[142:145], v[236:239], v[26:29]
	v_mfma_f32_16x16x32_bf16 v[22:25], v[134:137], v[244:247], v[22:25]
	v_mfma_f32_16x16x32_bf16 v[18:21], v[142:145], v[244:247], v[18:21]
	v_mfma_f32_16x16x32_bf16 v[62:65], v[146:149], v[214:217], v[62:65]
	v_mfma_f32_16x16x32_bf16 v[58:61], v[176:179], v[214:217], v[58:61]
	v_mfma_f32_16x16x32_bf16 v[54:57], v[146:149], v[224:227], v[54:57]
	v_mfma_f32_16x16x32_bf16 v[50:53], v[176:179], v[224:227], v[50:53]
	v_mfma_f32_16x16x32_bf16 v[14:17], v[146:149], v[232:235], v[14:17]
	v_mfma_f32_16x16x32_bf16 v[6:9], v[176:179], v[232:235], v[6:9]
	v_mfma_f32_16x16x32_bf16 v[10:13], v[146:149], v[240:243], v[10:13]
	v_mfma_f32_16x16x32_bf16 v[2:5], v[176:179], v[240:243], v[2:5]
	v_mfma_f32_16x16x32_bf16 v[62:65], v[172:175], v[218:221], v[62:65]
	v_mfma_f32_16x16x32_bf16 v[58:61], v[210:213], v[218:221], v[58:61]
	v_mfma_f32_16x16x32_bf16 v[54:57], v[172:175], v[228:231], v[54:57]
	v_mfma_f32_16x16x32_bf16 v[50:53], v[210:213], v[228:231], v[50:53]
	v_mfma_f32_16x16x32_bf16 v[14:17], v[172:175], v[236:239], v[14:17]
	v_mfma_f32_16x16x32_bf16 v[6:9], v[210:213], v[236:239], v[6:9]
	v_mfma_f32_16x16x32_bf16 v[10:13], v[172:175], v[244:247], v[10:13]
	v_mfma_f32_16x16x32_bf16 v[2:5], v[210:213], v[244:247], v[2:5]
	s_barrier
	s_setprio 0
	s_sleep 1
	s_add_i32 s16, s16, 2
	s_add_u32 s8, s8, 0x100
	s_addc_u32 s9, s9, 0
	s_add_u32 s14, s14, 0x100
	s_addc_u32 s15, s15, 0
	s_cmpk_gt_u32 s16, 0xa9
	s_cbranch_scc0 .LBB0_1040
	s_and_b64 vcc, exec, s[34:35]
	s_cbranch_vccz .LBB0_1043
	s_barrier
